# removed the remaining s_setprio 1/0 toggles around the MFMA groups (40 instructions)
# speedup vs baseline: 1.0103x; 1.0103x over previous
; #define PG8_STAGE(bufoff, gbase, voff) do { _Pragma("unroll") for (int _i = 0; _i < 2; ++_i) \
;         __builtin_amdgcn_global_load_lds((const unsigned*)((const char*)(gbase) + (voff)[_i]), (LAS unsigned*)(lds + (bufoff) + ldsw + _i * 8192), 16, 0, 0); } while (0)
; #define PG8_LDA(dst, b, h) do { _Pragma("unroll") for (int m = 0; m < 4; ++m) _Pragma("unroll") for (int k = 0; k < 2; ++k) dst[m][k] = *(const LAS bf16x8*)(lds + PG8_SA(b, h) + aoff + m * 2048 + k * 1024); } while (0)
; #define PG8_LDB(dst, b, h) do { _Pragma("unroll") for (int n = 0; n < 2; ++n) _Pragma("unroll") for (int k = 0; k < 2; ++k) dst[n][k] = *(const LAS bf16x8*)(lds + PG8_SB(b, h) + boff + n * 2048 + k * 1024); } while (0)
; #define PG8_MMA(ai, bj, At, Bt) do { __builtin_amdgcn_s_setprio(1); _Pragma("unroll") for (int m = 0; m < 4; ++m) _Pragma("unroll") for (int n = 0; n < 2; ++n) _Pragma("unroll") for (int k = 0; k < 2; ++k) \
;         acc[ai][bj][m][n] = __builtin_amdgcn_mfma_f32_16x16x32_bf16(Bt[n][k], At[m][k], acc[ai][bj][m][n], 0, 0, 0); __builtin_amdgcn_s_setprio(0); } while (0)
; #define PG8_WAIT_V(n) asm volatile("s_waitcnt vmcnt(" #n ")" ::: "memory")
; #define PG8_WAIT_L(n) asm volatile("s_waitcnt lgkmcnt(" #n ")" ::: "memory")
; #define PG8_BAR __builtin_amdgcn_s_barrier()
; #define PG8_SCHED __builtin_amdgcn_sched_barrier(0)
; template <class Epi, class Sched>
; DI void gemm_phase(const int wv, LAS unsigned char* lds, const int lda, const int ldb, const int K, const Sched& S, const Epi& E) {
;     ...
;             const bool last = (t == nt - 2);
;             const char* a1 = cA + (size_t)(t + 1) * kstep;
;             const char* a2 = last ? nA : cA + (size_t)(t + 2) * kstep; const char* b2 = last ? nB : cB + (size_t)(t + 2) * kstep;
;             const char* a3 = a2 + kstep; const char* b3 = b2 + kstep;
;             PG8_LDB(B0, 0, 0); PG8_LDB(B1, 0, 1); PG8_SCHED; PG8_LDA(At, 0, 0); PG8_STAGE(PG8_SA(1, 1), a1 + hstepA, voffA);
;             PG8_WAIT_V(8); PG8_WAIT_L(0); PG8_BAR; PG8_MMA(0, 0, At, B0); PG8_MMA(0, 1, At, B1); PG8_BAR; PG8_SCHED;
;             PG8_LDA(At, 0, 1); PG8_STAGE(PG8_SB(0, 0), b2, voffB); PG8_STAGE(PG8_SB(0, 1), b2 + hstepB, voffB); PG8_STAGE(PG8_SA(0, 0), a2, voffA);
;             PG8_WAIT_V(8); PG8_WAIT_L(0); PG8_BAR; PG8_MMA(1, 0, At, B0); PG8_MMA(1, 1, At, B1); PG8_BAR; PG8_SCHED;
.LBB0_285:
	s_add_u32 s20, s18, 0xfff80080
	s_addc_u32 s21, s19, -1
	s_add_i32 s42, 0, 0x10000
	s_cmp_eq_u32 s41, 28
	s_cselect_b32 s23, s15, s21
	s_cselect_b32 s22, s14, s20
	v_add_u32_e32 v143, s42, v139
	s_cselect_b32 s21, s17, s40
	s_cselect_b32 s20, s16, s13
	s_add_i32 s44, 0, 0x14000
	ds_read_b128 v[144:147], v143
	ds_read_b128 v[148:151], v143 offset:1024
	ds_read_b128 v[152:155], v143 offset:2048
	ds_read_b128 v[156:159], v143 offset:3072
	v_add_u32_e32 v143, s44, v139
	ds_read_b128 v[168:171], v143
	ds_read_b128 v[172:175], v143 offset:1024
	ds_read_b128 v[176:179], v143 offset:2048
	ds_read_b128 v[180:183], v143 offset:3072
	v_lshl_add_u64 v[162:163], s[18:19], 0, v[136:137]
	s_add_i32 m0, s29, 0xc000
	ds_read_b128 v[184:187], v142
	ds_read_b128 v[188:191], v142 offset:1024
	ds_read_b128 v[192:195], v142 offset:2048
	ds_read_b128 v[196:199], v142 offset:3072
	ds_read_b128 v[210:213], v142 offset:4096
	ds_read_b128 v[214:217], v142 offset:5120
	ds_read_b128 v[218:221], v142 offset:6144
	ds_read_b128 v[222:225], v142 offset:7168
	global_load_lds_dwordx4 v[162:163], off
	v_lshl_add_u64 v[162:163], s[18:19], 0, v[134:135]
	s_add_i32 m0, s29, 0xe000
	s_nop 0
	global_load_lds_dwordx4 v[162:163], off
	s_waitcnt vmcnt(8) lgkmcnt(0)
	s_barrier
	v_mfma_f32_16x16x32_bf16 v[124:127], v[144:147], v[184:187], v[124:127]
	v_mfma_f32_16x16x32_bf16 v[120:123], v[152:155], v[184:187], v[120:123]
	v_mfma_f32_16x16x32_bf16 v[116:119], v[144:147], v[192:195], v[116:119]
	v_mfma_f32_16x16x32_bf16 v[112:115], v[152:155], v[192:195], v[112:115]
	v_mfma_f32_16x16x32_bf16 v[100:103], v[144:147], v[210:213], v[100:103]
	v_mfma_f32_16x16x32_bf16 v[96:99], v[152:155], v[210:213], v[96:99]
	v_mfma_f32_16x16x32_bf16 v[88:91], v[144:147], v[218:221], v[88:91]
	v_mfma_f32_16x16x32_bf16 v[80:83], v[152:155], v[218:221], v[80:83]
	v_mfma_f32_16x16x32_bf16 v[124:127], v[148:151], v[188:191], v[124:127]
	v_mfma_f32_16x16x32_bf16 v[120:123], v[156:159], v[188:191], v[120:123]
	v_mfma_f32_16x16x32_bf16 v[116:119], v[148:151], v[196:199], v[116:119]
	v_mfma_f32_16x16x32_bf16 v[112:115], v[156:159], v[196:199], v[112:115]
	v_mfma_f32_16x16x32_bf16 v[100:103], v[148:151], v[214:217], v[100:103]
	v_mfma_f32_16x16x32_bf16 v[96:99], v[156:159], v[214:217], v[96:99]
	v_mfma_f32_16x16x32_bf16 v[88:91], v[148:151], v[222:225], v[88:91]
	v_mfma_f32_16x16x32_bf16 v[80:83], v[156:159], v[222:225], v[80:83]
	v_mfma_f32_16x16x32_bf16 v[108:111], v[168:171], v[184:187], v[108:111]
	v_mfma_f32_16x16x32_bf16 v[104:107], v[176:179], v[184:187], v[104:107]
	v_mfma_f32_16x16x32_bf16 v[92:95], v[168:171], v[192:195], v[92:95]
	v_mfma_f32_16x16x32_bf16 v[84:87], v[176:179], v[192:195], v[84:87]
	v_mfma_f32_16x16x32_bf16 v[76:79], v[168:171], v[210:213], v[76:79]
	v_mfma_f32_16x16x32_bf16 v[72:75], v[176:179], v[210:213], v[72:75]
	v_mfma_f32_16x16x32_bf16 v[68:71], v[168:171], v[218:221], v[68:71]
	v_mfma_f32_16x16x32_bf16 v[64:67], v[176:179], v[218:221], v[64:67]
	v_mfma_f32_16x16x32_bf16 v[108:111], v[172:175], v[188:191], v[108:111]
	v_mfma_f32_16x16x32_bf16 v[104:107], v[180:183], v[188:191], v[104:107]
	v_mfma_f32_16x16x32_bf16 v[92:95], v[172:175], v[196:199], v[92:95]
	v_mfma_f32_16x16x32_bf16 v[84:87], v[180:183], v[196:199], v[84:87]
	v_mfma_f32_16x16x32_bf16 v[76:79], v[172:175], v[214:217], v[76:79]
	v_mfma_f32_16x16x32_bf16 v[72:75], v[180:183], v[214:217], v[72:75]
	v_mfma_f32_16x16x32_bf16 v[68:71], v[172:175], v[222:225], v[68:71]
	v_mfma_f32_16x16x32_bf16 v[64:67], v[180:183], v[222:225], v[64:67]
	s_barrier
	s_add_i32 s42, s42, s28
	v_lshl_add_u64 v[162:163], s[20:21], 0, v[160:161]
	s_mov_b32 m0, s42
	ds_read_b128 v[184:187], v142 offset:16384
	ds_read_b128 v[188:191], v142 offset:17408
	ds_read_b128 v[192:195], v142 offset:18432
	ds_read_b128 v[196:199], v142 offset:19456
	ds_read_b128 v[210:213], v142 offset:20480
	ds_read_b128 v[214:217], v142 offset:21504
	ds_read_b128 v[218:221], v142 offset:22528
	ds_read_b128 v[222:225], v142 offset:23552
	global_load_lds_dwordx4 v[162:163], off
	s_add_i32 m0, s42, 0x2000
	s_add_u32 s42, s20, 0x80000
	v_lshl_add_u64 v[164:165], s[20:21], 0, v[128:129]
	s_addc_u32 s43, s21, 0
	s_add_i32 s44, s44, s28
	global_load_lds_dwordx4 v[164:165], off
	v_lshl_add_u64 v[226:227], s[42:43], 0, v[160:161]
	s_mov_b32 m0, s44
	v_lshl_add_u64 v[228:229], s[22:23], 0, v[130:131]
	global_load_lds_dwordx4 v[226:227], off
	v_lshl_add_u64 v[226:227], s[42:43], 0, v[128:129]
	s_add_i32 m0, s44, 0x2000
	s_nop 0
	global_load_lds_dwordx4 v[226:227], off
	v_lshl_add_u64 v[226:227], s[22:23], 0, v[132:133]
	s_mov_b32 m0, s29
	s_nop 0
	global_load_lds_dwordx4 v[226:227], off
	s_mov_b32 m0, s30
	s_nop 0
	global_load_lds_dwordx4 v[228:229], off
	s_waitcnt vmcnt(8) lgkmcnt(0)
	s_barrier
; #define PG8_STAGE(bufoff, gbase, voff) do { _Pragma("unroll") for (int _i = 0; _i < 2; ++_i) \
;         __builtin_amdgcn_global_load_lds((const unsigned*)((const char*)(gbase) + (voff)[_i]), (LAS unsigned*)(lds + (bufoff) + ldsw + _i * 8192), 16, 0, 0); } while (0)
; #define PG8_LDA(dst, b, h) do { _Pragma("unroll") for (int m = 0; m < 4; ++m) _Pragma("unroll") for (int k = 0; k < 2; ++k) dst[m][k] = *(const LAS bf16x8*)(lds + PG8_SA(b, h) + aoff + m * 2048 + k * 1024); } while (0)
; #define PG8_LDB(dst, b, h) do { _Pragma("unroll") for (int n = 0; n < 2; ++n) _Pragma("unroll") for (int k = 0; k < 2; ++k) dst[n][k] = *(const LAS bf16x8*)(lds + PG8_SB(b, h) + boff + n * 2048 + k * 1024); } while (0)
; #define PG8_MMA(ai, bj, At, Bt) do { __builtin_amdgcn_s_setprio(1); _Pragma("unroll") for (int m = 0; m < 4; ++m) _Pragma("unroll") for (int n = 0; n < 2; ++n) _Pragma("unroll") for (int k = 0; k < 2; ++k) \
;         acc[ai][bj][m][n] = __builtin_amdgcn_mfma_f32_16x16x32_bf16(Bt[n][k], At[m][k], acc[ai][bj][m][n], 0, 0, 0); __builtin_amdgcn_s_setprio(0); } while (0)
; #define PG8_WAIT_V(n) asm volatile("s_waitcnt vmcnt(" #n ")" ::: "memory")
; #define PG8_WAIT_L(n) asm volatile("s_waitcnt lgkmcnt(" #n ")" ::: "memory")
; #define PG8_BAR __builtin_amdgcn_s_barrier()
; #define PG8_SCHED __builtin_amdgcn_sched_barrier(0)
; template <class Epi, class Sched>
; DI void gemm_phase(const int wv, LAS unsigned char* lds, const int lda, const int ldb, const int K, const Sched& S, const Epi& E) {
;     ...
;             PG8_WAIT_V(8); PG8_WAIT_L(0); PG8_BAR; PG8_MMA(1, 0, At, B0); PG8_MMA(1, 1, At, B1); PG8_BAR; PG8_SCHED;
;             PG8_LDB(B0, 1, 0); PG8_LDB(B1, 1, 1); PG8_SCHED; PG8_LDA(At, 1, 0); PG8_STAGE(PG8_SA(0, 1), a2 + hstepA, voffA);
;             PG8_WAIT_V(8); PG8_WAIT_L(0); PG8_BAR; PG8_MMA(0, 0, At, B0); PG8_MMA(0, 1, At, B1); PG8_BAR; PG8_SCHED;
	v_mfma_f32_16x16x32_bf16 v[60:63], v[144:147], v[184:187], v[60:63]
	v_mfma_f32_16x16x32_bf16 v[56:59], v[152:155], v[184:187], v[56:59]
	v_mfma_f32_16x16x32_bf16 v[52:55], v[144:147], v[192:195], v[52:55]
	v_mfma_f32_16x16x32_bf16 v[48:51], v[152:155], v[192:195], v[48:51]
	v_mfma_f32_16x16x32_bf16 v[44:47], v[144:147], v[210:213], v[44:47]
	v_mfma_f32_16x16x32_bf16 v[36:39], v[152:155], v[210:213], v[36:39]
	v_mfma_f32_16x16x32_bf16 v[28:31], v[144:147], v[218:221], v[28:31]
	v_mfma_f32_16x16x32_bf16 v[20:23], v[152:155], v[218:221], v[20:23]
	v_mfma_f32_16x16x32_bf16 v[60:63], v[148:151], v[188:191], v[60:63]
	v_mfma_f32_16x16x32_bf16 v[56:59], v[156:159], v[188:191], v[56:59]
	v_mfma_f32_16x16x32_bf16 v[52:55], v[148:151], v[196:199], v[52:55]
	v_mfma_f32_16x16x32_bf16 v[48:51], v[156:159], v[196:199], v[48:51]
	v_mfma_f32_16x16x32_bf16 v[44:47], v[148:151], v[214:217], v[44:47]
	v_mfma_f32_16x16x32_bf16 v[36:39], v[156:159], v[214:217], v[36:39]
	v_mfma_f32_16x16x32_bf16 v[28:31], v[148:151], v[222:225], v[28:31]
	v_mfma_f32_16x16x32_bf16 v[20:23], v[156:159], v[222:225], v[20:23]
	v_mfma_f32_16x16x32_bf16 v[40:43], v[168:171], v[184:187], v[40:43]
	v_mfma_f32_16x16x32_bf16 v[32:35], v[176:179], v[184:187], v[32:35]
	v_mfma_f32_16x16x32_bf16 v[24:27], v[168:171], v[192:195], v[24:27]
	v_mfma_f32_16x16x32_bf16 v[16:19], v[176:179], v[192:195], v[16:19]
	v_mfma_f32_16x16x32_bf16 v[12:15], v[168:171], v[210:213], v[12:15]
	v_mfma_f32_16x16x32_bf16 v[8:11], v[176:179], v[210:213], v[8:11]
	v_mfma_f32_16x16x32_bf16 v[4:7], v[168:171], v[218:221], v[4:7]
	v_mfma_f32_16x16x32_bf16 v[0:3], v[176:179], v[218:221], v[0:3]
	v_mfma_f32_16x16x32_bf16 v[40:43], v[172:175], v[188:191], v[40:43]
	v_mfma_f32_16x16x32_bf16 v[32:35], v[180:183], v[188:191], v[32:35]
	v_mfma_f32_16x16x32_bf16 v[24:27], v[172:175], v[196:199], v[24:27]
	v_mfma_f32_16x16x32_bf16 v[16:19], v[180:183], v[196:199], v[16:19]
	v_mfma_f32_16x16x32_bf16 v[12:15], v[172:175], v[214:217], v[12:15]
	v_mfma_f32_16x16x32_bf16 v[8:11], v[180:183], v[214:217], v[8:11]
	v_mfma_f32_16x16x32_bf16 v[4:7], v[172:175], v[222:225], v[4:7]
	v_mfma_f32_16x16x32_bf16 v[0:3], v[180:183], v[222:225], v[0:3]
	s_barrier
	s_add_i32 s42, 0, 0x18000
	v_add_u32_e32 v143, s42, v139
	s_add_i32 s43, 0, 0x1c000
	ds_read_b128 v[144:147], v143
	ds_read_b128 v[148:151], v143 offset:1024
	ds_read_b128 v[152:155], v143 offset:2048
	ds_read_b128 v[156:159], v143 offset:3072
	v_add_u32_e32 v143, s43, v139
	ds_read_b128 v[168:171], v143
	ds_read_b128 v[172:175], v143 offset:1024
	ds_read_b128 v[176:179], v143 offset:2048
	ds_read_b128 v[180:183], v143 offset:3072
	s_add_u32 s22, s22, 0x80000
	s_addc_u32 s23, s23, 0
	s_mov_b32 m0, s31
	v_lshl_add_u64 v[230:231], s[22:23], 0, v[132:133]
	ds_read_b128 v[184:187], v142 offset:32768
	ds_read_b128 v[188:191], v142 offset:33792
	ds_read_b128 v[192:195], v142 offset:34816
	ds_read_b128 v[196:199], v142 offset:35840
	ds_read_b128 v[210:213], v142 offset:36864
	ds_read_b128 v[214:217], v142 offset:37888
	ds_read_b128 v[218:221], v142 offset:38912
	ds_read_b128 v[222:225], v142 offset:39936
	global_load_lds_dwordx4 v[230:231], off
	v_lshl_add_u64 v[230:231], s[22:23], 0, v[130:131]
	s_mov_b32 m0, s34
	s_nop 0
	global_load_lds_dwordx4 v[230:231], off
	s_waitcnt vmcnt(8) lgkmcnt(0)
	s_barrier
	v_mfma_f32_16x16x32_bf16 v[124:127], v[144:147], v[184:187], v[124:127]
	v_mfma_f32_16x16x32_bf16 v[120:123], v[152:155], v[184:187], v[120:123]
	v_mfma_f32_16x16x32_bf16 v[116:119], v[144:147], v[192:195], v[116:119]
	v_mfma_f32_16x16x32_bf16 v[112:115], v[152:155], v[192:195], v[112:115]
	v_mfma_f32_16x16x32_bf16 v[100:103], v[144:147], v[210:213], v[100:103]
	v_mfma_f32_16x16x32_bf16 v[96:99], v[152:155], v[210:213], v[96:99]
	v_mfma_f32_16x16x32_bf16 v[88:91], v[144:147], v[218:221], v[88:91]
	v_mfma_f32_16x16x32_bf16 v[80:83], v[152:155], v[218:221], v[80:83]
	v_mfma_f32_16x16x32_bf16 v[124:127], v[148:151], v[188:191], v[124:127]
	v_mfma_f32_16x16x32_bf16 v[120:123], v[156:159], v[188:191], v[120:123]
	v_mfma_f32_16x16x32_bf16 v[116:119], v[148:151], v[196:199], v[116:119]
	v_mfma_f32_16x16x32_bf16 v[112:115], v[156:159], v[196:199], v[112:115]
	v_mfma_f32_16x16x32_bf16 v[100:103], v[148:151], v[214:217], v[100:103]
	v_mfma_f32_16x16x32_bf16 v[96:99], v[156:159], v[214:217], v[96:99]
	v_mfma_f32_16x16x32_bf16 v[88:91], v[148:151], v[222:225], v[88:91]
	v_mfma_f32_16x16x32_bf16 v[80:83], v[156:159], v[222:225], v[80:83]
	v_mfma_f32_16x16x32_bf16 v[108:111], v[168:171], v[184:187], v[108:111]
	v_mfma_f32_16x16x32_bf16 v[104:107], v[176:179], v[184:187], v[104:107]
	v_mfma_f32_16x16x32_bf16 v[92:95], v[168:171], v[192:195], v[92:95]
	v_mfma_f32_16x16x32_bf16 v[84:87], v[176:179], v[192:195], v[84:87]
	v_mfma_f32_16x16x32_bf16 v[76:79], v[168:171], v[210:213], v[76:79]
	v_mfma_f32_16x16x32_bf16 v[72:75], v[176:179], v[210:213], v[72:75]
	v_mfma_f32_16x16x32_bf16 v[68:71], v[168:171], v[218:221], v[68:71]
	v_mfma_f32_16x16x32_bf16 v[64:67], v[176:179], v[218:221], v[64:67]
	v_mfma_f32_16x16x32_bf16 v[108:111], v[172:175], v[188:191], v[108:111]
	v_mfma_f32_16x16x32_bf16 v[104:107], v[180:183], v[188:191], v[104:107]
	v_mfma_f32_16x16x32_bf16 v[92:95], v[172:175], v[196:199], v[92:95]
	v_mfma_f32_16x16x32_bf16 v[84:87], v[180:183], v[196:199], v[84:87]
	v_mfma_f32_16x16x32_bf16 v[76:79], v[172:175], v[214:217], v[76:79]
	v_mfma_f32_16x16x32_bf16 v[72:75], v[180:183], v[214:217], v[72:75]
	v_mfma_f32_16x16x32_bf16 v[68:71], v[172:175], v[222:225], v[68:71]
	v_mfma_f32_16x16x32_bf16 v[64:67], v[180:183], v[222:225], v[64:67]
	s_barrier
; #define PG8_STAGE(bufoff, gbase, voff) do { _Pragma("unroll") for (int _i = 0; _i < 2; ++_i) \
;         __builtin_amdgcn_global_load_lds((const unsigned*)((const char*)(gbase) + (voff)[_i]), (LAS unsigned*)(lds + (bufoff) + ldsw + _i * 8192), 16, 0, 0); } while (0)
; #define PG8_LDA(dst, b, h) do { _Pragma("unroll") for (int m = 0; m < 4; ++m) _Pragma("unroll") for (int k = 0; k < 2; ++k) dst[m][k] = *(const LAS bf16x8*)(lds + PG8_SA(b, h) + aoff + m * 2048 + k * 1024); } while (0)
; #define PG8_MMA(ai, bj, At, Bt) do { __builtin_amdgcn_s_setprio(1); _Pragma("unroll") for (int m = 0; m < 4; ++m) _Pragma("unroll") for (int n = 0; n < 2; ++n) _Pragma("unroll") for (int k = 0; k < 2; ++k) \
;         acc[ai][bj][m][n] = __builtin_amdgcn_mfma_f32_16x16x32_bf16(Bt[n][k], At[m][k], acc[ai][bj][m][n], 0, 0, 0); __builtin_amdgcn_s_setprio(0); } while (0)
; #define PG8_WAIT_V(n) asm volatile("s_waitcnt vmcnt(" #n ")" ::: "memory")
; #define PG8_WAIT_L(n) asm volatile("s_waitcnt lgkmcnt(" #n ")" ::: "memory")
; #define PG8_BAR __builtin_amdgcn_s_barrier()
; #define PG8_SCHED __builtin_amdgcn_sched_barrier(0)
; template <class Epi, class Sched>
; DI void gemm_phase(const int wv, LAS unsigned char* lds, const int lda, const int ldb, const int K, const Sched& S, const Epi& E) {
;     ...
;             PG8_LDA(At, 1, 1); PG8_STAGE(PG8_SB(1, 0), b3, voffB); PG8_STAGE(PG8_SB(1, 1), b3 + hstepB, voffB); PG8_STAGE(PG8_SA(1, 0), a3, voffA);
;             PG8_WAIT_V(8); PG8_WAIT_L(0); PG8_BAR; PG8_MMA(1, 0, At, B0); PG8_MMA(1, 1, At, B1); PG8_BAR; PG8_SCHED;
;         }
;         if (wr == 0) PG8_BAR;
	s_add_i32 s22, s42, s28
	v_lshl_add_u64 v[162:163], v[162:163], 0, s[78:79]
	s_mov_b32 m0, s22
	ds_read_b128 v[184:187], v142 offset:49152
	ds_read_b128 v[188:191], v142 offset:50176
	ds_read_b128 v[192:195], v142 offset:51200
	ds_read_b128 v[196:199], v142 offset:52224
	ds_read_b128 v[210:213], v142 offset:53248
	ds_read_b128 v[214:217], v142 offset:54272
	ds_read_b128 v[218:221], v142 offset:55296
	ds_read_b128 v[222:225], v142 offset:56320
	global_load_lds_dwordx4 v[162:163], off
	s_add_i32 m0, s22, 0x2000
	s_add_u32 s20, s20, 0x80080
	v_lshl_add_u64 v[162:163], v[164:165], 0, s[78:79]
	s_addc_u32 s21, s21, 0
	s_add_i32 s22, s43, s28
	global_load_lds_dwordx4 v[162:163], off
	v_lshl_add_u64 v[162:163], s[20:21], 0, v[160:161]
	s_mov_b32 m0, s22
	s_nop 0
	global_load_lds_dwordx4 v[162:163], off
	v_lshl_add_u64 v[162:163], s[20:21], 0, v[128:129]
	s_add_i32 m0, s22, 0x2000
	s_nop 0
	global_load_lds_dwordx4 v[162:163], off
	v_lshl_add_u64 v[162:163], v[226:227], 0, s[78:79]
	s_mov_b32 m0, s35
	s_nop 0
	global_load_lds_dwordx4 v[162:163], off
	v_lshl_add_u64 v[162:163], v[228:229], 0, s[78:79]
	s_mov_b32 m0, s36
	s_nop 0
	global_load_lds_dwordx4 v[162:163], off
	s_waitcnt vmcnt(8) lgkmcnt(0)
	s_barrier
	v_mfma_f32_16x16x32_bf16 v[60:63], v[144:147], v[184:187], v[60:63]
	v_mfma_f32_16x16x32_bf16 v[56:59], v[152:155], v[184:187], v[56:59]
	v_mfma_f32_16x16x32_bf16 v[52:55], v[144:147], v[192:195], v[52:55]
	v_mfma_f32_16x16x32_bf16 v[48:51], v[152:155], v[192:195], v[48:51]
	v_mfma_f32_16x16x32_bf16 v[44:47], v[144:147], v[210:213], v[44:47]
	v_mfma_f32_16x16x32_bf16 v[36:39], v[152:155], v[210:213], v[36:39]
	v_mfma_f32_16x16x32_bf16 v[28:31], v[144:147], v[218:221], v[28:31]
	v_mfma_f32_16x16x32_bf16 v[20:23], v[152:155], v[218:221], v[20:23]
	v_mfma_f32_16x16x32_bf16 v[60:63], v[148:151], v[188:191], v[60:63]
	v_mfma_f32_16x16x32_bf16 v[56:59], v[156:159], v[188:191], v[56:59]
	v_mfma_f32_16x16x32_bf16 v[52:55], v[148:151], v[196:199], v[52:55]
	v_mfma_f32_16x16x32_bf16 v[48:51], v[156:159], v[196:199], v[48:51]
	v_mfma_f32_16x16x32_bf16 v[44:47], v[148:151], v[214:217], v[44:47]
	v_mfma_f32_16x16x32_bf16 v[36:39], v[156:159], v[214:217], v[36:39]
	v_mfma_f32_16x16x32_bf16 v[28:31], v[148:151], v[222:225], v[28:31]
	v_mfma_f32_16x16x32_bf16 v[20:23], v[156:159], v[222:225], v[20:23]
	v_mfma_f32_16x16x32_bf16 v[40:43], v[168:171], v[184:187], v[40:43]
	v_mfma_f32_16x16x32_bf16 v[32:35], v[176:179], v[184:187], v[32:35]
	v_mfma_f32_16x16x32_bf16 v[24:27], v[168:171], v[192:195], v[24:27]
	v_mfma_f32_16x16x32_bf16 v[16:19], v[176:179], v[192:195], v[16:19]
	v_mfma_f32_16x16x32_bf16 v[12:15], v[168:171], v[210:213], v[12:15]
	v_mfma_f32_16x16x32_bf16 v[8:11], v[176:179], v[210:213], v[8:11]
	v_mfma_f32_16x16x32_bf16 v[4:7], v[168:171], v[218:221], v[4:7]
	v_mfma_f32_16x16x32_bf16 v[0:3], v[176:179], v[218:221], v[0:3]
	v_mfma_f32_16x16x32_bf16 v[40:43], v[172:175], v[188:191], v[40:43]
	v_mfma_f32_16x16x32_bf16 v[32:35], v[180:183], v[188:191], v[32:35]
	v_mfma_f32_16x16x32_bf16 v[24:27], v[172:175], v[196:199], v[24:27]
	v_mfma_f32_16x16x32_bf16 v[16:19], v[180:183], v[196:199], v[16:19]
	v_mfma_f32_16x16x32_bf16 v[12:15], v[172:175], v[214:217], v[12:15]
	v_mfma_f32_16x16x32_bf16 v[8:11], v[180:183], v[214:217], v[8:11]
	v_mfma_f32_16x16x32_bf16 v[4:7], v[172:175], v[222:225], v[4:7]
	v_mfma_f32_16x16x32_bf16 v[0:3], v[180:183], v[222:225], v[0:3]
	s_barrier
	s_add_i32 s41, s41, 2
	s_add_u32 s13, s13, 0x100
	s_addc_u32 s40, s40, 0
	s_add_u32 s18, s18, 0x100
	s_addc_u32 s19, s19, 0
	s_cmp_gt_u32 s41, 29
	s_cbranch_scc0 .LBB0_285
	s_and_b64 vcc, exec, s[10:11]
	s_cbranch_vccz .LBB0_288
	s_barrier

; #define PG8_STAGE(bufoff, gbase, voff) do { _Pragma("unroll") for (int _i = 0; _i < 2; ++_i) \
;         __builtin_amdgcn_global_load_lds((const unsigned*)((const char*)(gbase) + (voff)[_i]), (LAS unsigned*)(lds + (bufoff) + ldsw + _i * 8192), 16, 0, 0); } while (0)
; #define PG8_LDA(dst, b, h) do { _Pragma("unroll") for (int m = 0; m < 4; ++m) _Pragma("unroll") for (int k = 0; k < 2; ++k) dst[m][k] = *(const LAS bf16x8*)(lds + PG8_SA(b, h) + aoff + m * 2048 + k * 1024); } while (0)
; #define PG8_LDB(dst, b, h) do { _Pragma("unroll") for (int n = 0; n < 2; ++n) _Pragma("unroll") for (int k = 0; k < 2; ++k) dst[n][k] = *(const LAS bf16x8*)(lds + PG8_SB(b, h) + boff + n * 2048 + k * 1024); } while (0)
; #define PG8_MMA(ai, bj, At, Bt) do { __builtin_amdgcn_s_setprio(1); _Pragma("unroll") for (int m = 0; m < 4; ++m) _Pragma("unroll") for (int n = 0; n < 2; ++n) _Pragma("unroll") for (int k = 0; k < 2; ++k) \
;         acc[ai][bj][m][n] = __builtin_amdgcn_mfma_f32_16x16x32_bf16(Bt[n][k], At[m][k], acc[ai][bj][m][n], 0, 0, 0); __builtin_amdgcn_s_setprio(0); } while (0)
; #define PG8_WAIT_V(n) asm volatile("s_waitcnt vmcnt(" #n ")" ::: "memory")
; template <class Epi, class Sched>
; DI void gemm_phase(const int wv, LAS unsigned char* lds, const int lda, const int ldb, const int K, const Sched& S, const Epi& E) {
;     ...
;         const bool has_next = S.next(ui + 1, nxt);
;         const char* nA = has_next ? nxt.a : cA; const char* nB = has_next ? nxt.b : cB;
; #pragma unroll 1
;         for (int t = 0; t < nt; t += 2) {
;             const bool last = (t == nt - 2);
;             const char* a1 = cA + (size_t)(t + 1) * kstep;
;             const char* a2 = last ? nA : cA + (size_t)(t + 2) * kstep; const char* b2 = last ? nB : cB + (size_t)(t + 2) * kstep;
;             const char* a3 = a2 + kstep; const char* b3 = b2 + kstep;
;             PG8_LDB(B0, 0, 0); PG8_LDB(B1, 0, 1); PG8_SCHED; PG8_LDA(At, 0, 0); PG8_STAGE(PG8_SA(1, 1), a1 + hstepA, voffA);
;             PG8_WAIT_V(8); PG8_WAIT_L(0); PG8_BAR; PG8_MMA(0, 0, At, B0); PG8_MMA(0, 1, At, B1); PG8_BAR; PG8_SCHED;
;             PG8_LDA(At, 0, 1); PG8_STAGE(PG8_SB(0, 0), b2, voffB); PG8_STAGE(PG8_SB(0, 1), b2 + hstepB, voffB); PG8_STAGE(PG8_SA(0, 0), a2, voffA);
;             PG8_WAIT_V(8); PG8_WAIT_L(0); PG8_BAR; PG8_MMA(1, 0, At, B0); PG8_MMA(1, 1, At, B1); PG8_BAR; PG8_SCHED;
.LBB0_516:
	s_add_u32 s14, s2, s8
	s_addc_u32 s15, s3, s9
	s_add_u32 s12, s14, 0x100
	s_addc_u32 s13, s15, 0
	s_and_b64 s[10:11], s[6:7], exec
	s_cselect_b32 s11, s3, s13
	s_cselect_b32 s10, s2, s12
	s_add_u32 s8, s0, s8
	s_addc_u32 s9, s1, s9
	s_add_u32 s8, s8, 0x100
	s_addc_u32 s9, s9, 0
	s_add_i32 s39, 0, 0x10000
	s_and_b64 s[6:7], s[6:7], exec
	s_cselect_b32 s13, s1, s9
	s_cselect_b32 s12, s0, s8
	s_add_i32 s7, 0, 0x14000
	s_add_u32 s16, s14, 0x40080
	s_addc_u32 s17, s15, 0
	s_add_i32 s38, s39, s21
	s_add_i32 m0, s22, 0xc000
	s_add_i32 s41, s22, 0xe000
	s_add_i32 s35, s38, 0x2000
	s_add_u32 s14, s12, 0x10000
	v_add_u32_e32 v150, s39, v136
	v_add_u32_e32 v158, s7, v136
	s_addc_u32 s15, s13, 0
	s_add_i32 s37, s7, s21
	ds_read_b128 v[138:141], v150
	ds_read_b128 v[142:145], v150 offset:1024
	ds_read_b128 v[146:149], v150 offset:2048
	ds_read_b128 v[150:153], v150 offset:3072
	ds_read_b128 v[154:157], v158
	ds_read_b128 v[162:165], v158 offset:1024
	ds_read_b128 v[168:171], v158 offset:2048
	ds_read_b128 v[172:175], v158 offset:3072
	s_add_i32 s36, s37, 0x2000
	s_add_i32 s34, 0, 0x18000
	s_add_i32 s31, 0, 0x1c000
	s_add_u32 s8, s10, 0x40000
	s_addc_u32 s9, s11, 0
	s_add_i32 s30, s34, s21
	s_add_i32 s29, s30, 0x2000
	s_add_u32 s6, s12, 0x10080
	s_addc_u32 s7, s13, 0
	s_add_i32 s40, s31, s21
	s_add_i32 s39, s40, 0x2000
	v_lshl_add_u64 v[158:159], s[16:17], 0, v[128:129]
	ds_read_b128 v[176:179], v137
	ds_read_b128 v[180:183], v137 offset:1024
	ds_read_b128 v[184:187], v137 offset:2048
	ds_read_b128 v[188:191], v137 offset:3072
	ds_read_b128 v[192:195], v137 offset:4096
	ds_read_b128 v[196:199], v137 offset:5120
	ds_read_b128 v[210:213], v137 offset:6144
	ds_read_b128 v[214:217], v137 offset:7168
	global_load_lds_dwordx4 v[158:159], off
	v_lshl_add_u64 v[158:159], s[16:17], 0, v[130:131]
	s_mov_b32 m0, s41
	s_nop 0
	global_load_lds_dwordx4 v[158:159], off
	s_waitcnt vmcnt(8) lgkmcnt(0)
	s_barrier
	v_mfma_f32_16x16x32_bf16 v[124:127], v[138:141], v[176:179], v[124:127]
	v_mfma_f32_16x16x32_bf16 v[120:123], v[146:149], v[176:179], v[120:123]
	v_mfma_f32_16x16x32_bf16 v[116:119], v[138:141], v[184:187], v[116:119]
	v_mfma_f32_16x16x32_bf16 v[112:115], v[146:149], v[184:187], v[112:115]
	v_mfma_f32_16x16x32_bf16 v[100:103], v[138:141], v[192:195], v[100:103]
	v_mfma_f32_16x16x32_bf16 v[96:99], v[146:149], v[192:195], v[96:99]
	v_mfma_f32_16x16x32_bf16 v[84:87], v[138:141], v[210:213], v[84:87]
	v_mfma_f32_16x16x32_bf16 v[80:83], v[146:149], v[210:213], v[80:83]
	v_mfma_f32_16x16x32_bf16 v[124:127], v[142:145], v[180:183], v[124:127]
	v_mfma_f32_16x16x32_bf16 v[120:123], v[150:153], v[180:183], v[120:123]
	v_mfma_f32_16x16x32_bf16 v[116:119], v[142:145], v[188:191], v[116:119]
	v_mfma_f32_16x16x32_bf16 v[112:115], v[150:153], v[188:191], v[112:115]
	v_mfma_f32_16x16x32_bf16 v[100:103], v[142:145], v[196:199], v[100:103]
	v_mfma_f32_16x16x32_bf16 v[96:99], v[150:153], v[196:199], v[96:99]
	v_mfma_f32_16x16x32_bf16 v[84:87], v[142:145], v[214:217], v[84:87]
	v_mfma_f32_16x16x32_bf16 v[80:83], v[150:153], v[214:217], v[80:83]
	v_mfma_f32_16x16x32_bf16 v[108:111], v[154:157], v[176:179], v[108:111]
	v_mfma_f32_16x16x32_bf16 v[104:107], v[168:171], v[176:179], v[104:107]
	v_mfma_f32_16x16x32_bf16 v[92:95], v[154:157], v[184:187], v[92:95]
	v_mfma_f32_16x16x32_bf16 v[88:91], v[168:171], v[184:187], v[88:91]
	v_mfma_f32_16x16x32_bf16 v[76:79], v[154:157], v[192:195], v[76:79]
	v_mfma_f32_16x16x32_bf16 v[72:75], v[168:171], v[192:195], v[72:75]
	v_mfma_f32_16x16x32_bf16 v[68:71], v[154:157], v[210:213], v[68:71]
	v_mfma_f32_16x16x32_bf16 v[64:67], v[168:171], v[210:213], v[64:67]
	v_mfma_f32_16x16x32_bf16 v[108:111], v[162:165], v[180:183], v[108:111]
	v_mfma_f32_16x16x32_bf16 v[104:107], v[172:175], v[180:183], v[104:107]
	v_mfma_f32_16x16x32_bf16 v[92:95], v[162:165], v[188:191], v[92:95]
	v_mfma_f32_16x16x32_bf16 v[88:91], v[172:175], v[188:191], v[88:91]
	v_mfma_f32_16x16x32_bf16 v[76:79], v[162:165], v[196:199], v[76:79]
	v_mfma_f32_16x16x32_bf16 v[72:75], v[172:175], v[196:199], v[72:75]
	v_mfma_f32_16x16x32_bf16 v[68:71], v[162:165], v[214:217], v[68:71]
	v_mfma_f32_16x16x32_bf16 v[64:67], v[172:175], v[214:217], v[64:67]
	s_barrier
	s_mov_b32 m0, s38
	v_lshl_add_u64 v[158:159], s[12:13], 0, v[160:161]
	ds_read_b128 v[176:179], v137 offset:16384
	ds_read_b128 v[180:183], v137 offset:17408
	ds_read_b128 v[184:187], v137 offset:18432
	ds_read_b128 v[188:191], v137 offset:19456
	ds_read_b128 v[192:195], v137 offset:20480
	ds_read_b128 v[196:199], v137 offset:21504
	ds_read_b128 v[210:213], v137 offset:22528
	ds_read_b128 v[214:217], v137 offset:23552
	global_load_lds_dwordx4 v[158:159], off
	v_lshl_add_u64 v[218:219], s[12:13], 0, v[132:133]
	s_mov_b32 m0, s35
	v_lshl_add_u64 v[220:221], s[14:15], 0, v[160:161]
	global_load_lds_dwordx4 v[218:219], off
	s_mov_b32 m0, s37
	v_lshl_add_u64 v[222:223], s[10:11], 0, v[130:131]
	global_load_lds_dwordx4 v[220:221], off
	v_lshl_add_u64 v[220:221], s[14:15], 0, v[132:133]
	s_mov_b32 m0, s36
	s_nop 0
	global_load_lds_dwordx4 v[220:221], off
	v_lshl_add_u64 v[220:221], s[10:11], 0, v[128:129]
	s_mov_b32 m0, s22
	s_nop 0
	global_load_lds_dwordx4 v[220:221], off
	s_mov_b32 m0, s23
	s_nop 0
	global_load_lds_dwordx4 v[222:223], off
	s_waitcnt vmcnt(8) lgkmcnt(0)
	s_barrier
; #define PG8_STAGE(bufoff, gbase, voff) do { _Pragma("unroll") for (int _i = 0; _i < 2; ++_i) \
;         __builtin_amdgcn_global_load_lds((const unsigned*)((const char*)(gbase) + (voff)[_i]), (LAS unsigned*)(lds + (bufoff) + ldsw + _i * 8192), 16, 0, 0); } while (0)
; #define PG8_LDA(dst, b, h) do { _Pragma("unroll") for (int m = 0; m < 4; ++m) _Pragma("unroll") for (int k = 0; k < 2; ++k) dst[m][k] = *(const LAS bf16x8*)(lds + PG8_SA(b, h) + aoff + m * 2048 + k * 1024); } while (0)
; #define PG8_LDB(dst, b, h) do { _Pragma("unroll") for (int n = 0; n < 2; ++n) _Pragma("unroll") for (int k = 0; k < 2; ++k) dst[n][k] = *(const LAS bf16x8*)(lds + PG8_SB(b, h) + boff + n * 2048 + k * 1024); } while (0)
; #define PG8_MMA(ai, bj, At, Bt) do { __builtin_amdgcn_s_setprio(1); _Pragma("unroll") for (int m = 0; m < 4; ++m) _Pragma("unroll") for (int n = 0; n < 2; ++n) _Pragma("unroll") for (int k = 0; k < 2; ++k) \
;         acc[ai][bj][m][n] = __builtin_amdgcn_mfma_f32_16x16x32_bf16(Bt[n][k], At[m][k], acc[ai][bj][m][n], 0, 0, 0); __builtin_amdgcn_s_setprio(0); } while (0)
; #define PG8_WAIT_V(n) asm volatile("s_waitcnt vmcnt(" #n ")" ::: "memory")
; #define PG8_WAIT_L(n) asm volatile("s_waitcnt lgkmcnt(" #n ")" ::: "memory")
; #define PG8_BAR __builtin_amdgcn_s_barrier()
; #define PG8_SCHED __builtin_amdgcn_sched_barrier(0)
; template <class Epi, class Sched>
; DI void gemm_phase(const int wv, LAS unsigned char* lds, const int lda, const int ldb, const int K, const Sched& S, const Epi& E) {
;     ...
;             PG8_WAIT_V(8); PG8_WAIT_L(0); PG8_BAR; PG8_MMA(1, 0, At, B0); PG8_MMA(1, 1, At, B1); PG8_BAR; PG8_SCHED;
;             PG8_LDB(B0, 1, 0); PG8_LDB(B1, 1, 1); PG8_SCHED; PG8_LDA(At, 1, 0); PG8_STAGE(PG8_SA(0, 1), a2 + hstepA, voffA);
;             PG8_WAIT_V(8); PG8_WAIT_L(0); PG8_BAR; PG8_MMA(0, 0, At, B0); PG8_MMA(0, 1, At, B1); PG8_BAR; PG8_SCHED;
;             PG8_LDA(At, 1, 1); PG8_STAGE(PG8_SB(1, 0), b3, voffB); PG8_STAGE(PG8_SB(1, 1), b3 + hstepB, voffB); PG8_STAGE(PG8_SA(1, 0), a3, voffA);
;             PG8_WAIT_V(8); PG8_WAIT_L(0); PG8_BAR; PG8_MMA(1, 0, At, B0); PG8_MMA(1, 1, At, B1); PG8_BAR; PG8_SCHED;
	v_mfma_f32_16x16x32_bf16 v[60:63], v[138:141], v[176:179], v[60:63]
	v_mfma_f32_16x16x32_bf16 v[56:59], v[146:149], v[176:179], v[56:59]
	v_mfma_f32_16x16x32_bf16 v[52:55], v[138:141], v[184:187], v[52:55]
	v_mfma_f32_16x16x32_bf16 v[48:51], v[146:149], v[184:187], v[48:51]
	v_mfma_f32_16x16x32_bf16 v[36:39], v[138:141], v[192:195], v[36:39]
	v_mfma_f32_16x16x32_bf16 v[32:35], v[146:149], v[192:195], v[32:35]
	v_mfma_f32_16x16x32_bf16 v[20:23], v[138:141], v[210:213], v[20:23]
	v_mfma_f32_16x16x32_bf16 v[16:19], v[146:149], v[210:213], v[16:19]
	v_mfma_f32_16x16x32_bf16 v[60:63], v[142:145], v[180:183], v[60:63]
	v_mfma_f32_16x16x32_bf16 v[56:59], v[150:153], v[180:183], v[56:59]
	v_mfma_f32_16x16x32_bf16 v[52:55], v[142:145], v[188:191], v[52:55]
	v_mfma_f32_16x16x32_bf16 v[48:51], v[150:153], v[188:191], v[48:51]
	v_mfma_f32_16x16x32_bf16 v[36:39], v[142:145], v[196:199], v[36:39]
	v_mfma_f32_16x16x32_bf16 v[32:35], v[150:153], v[196:199], v[32:35]
	v_mfma_f32_16x16x32_bf16 v[20:23], v[142:145], v[214:217], v[20:23]
	v_mfma_f32_16x16x32_bf16 v[16:19], v[150:153], v[214:217], v[16:19]
	v_mfma_f32_16x16x32_bf16 v[44:47], v[154:157], v[176:179], v[44:47]
	v_mfma_f32_16x16x32_bf16 v[40:43], v[168:171], v[176:179], v[40:43]
	v_mfma_f32_16x16x32_bf16 v[28:31], v[154:157], v[184:187], v[28:31]
	v_mfma_f32_16x16x32_bf16 v[24:27], v[168:171], v[184:187], v[24:27]
	v_mfma_f32_16x16x32_bf16 v[12:15], v[154:157], v[192:195], v[12:15]
	v_mfma_f32_16x16x32_bf16 v[8:11], v[168:171], v[192:195], v[8:11]
	v_mfma_f32_16x16x32_bf16 v[4:7], v[154:157], v[210:213], v[4:7]
	v_mfma_f32_16x16x32_bf16 v[0:3], v[168:171], v[210:213], v[0:3]
	v_mfma_f32_16x16x32_bf16 v[44:47], v[162:165], v[180:183], v[44:47]
	v_mfma_f32_16x16x32_bf16 v[40:43], v[172:175], v[180:183], v[40:43]
	v_mfma_f32_16x16x32_bf16 v[28:31], v[162:165], v[188:191], v[28:31]
	v_mfma_f32_16x16x32_bf16 v[24:27], v[172:175], v[188:191], v[24:27]
	v_mfma_f32_16x16x32_bf16 v[12:15], v[162:165], v[196:199], v[12:15]
	v_mfma_f32_16x16x32_bf16 v[8:11], v[172:175], v[196:199], v[8:11]
	v_mfma_f32_16x16x32_bf16 v[4:7], v[162:165], v[214:217], v[4:7]
	v_mfma_f32_16x16x32_bf16 v[0:3], v[172:175], v[214:217], v[0:3]
	s_barrier
	v_add_u32_e32 v150, s34, v136
	v_add_u32_e32 v172, s31, v136
	ds_read_b128 v[138:141], v150
	ds_read_b128 v[142:145], v150 offset:1024
	ds_read_b128 v[146:149], v150 offset:2048
	ds_read_b128 v[150:153], v150 offset:3072
	ds_read_b128 v[154:157], v172
	ds_read_b128 v[162:165], v172 offset:1024
	ds_read_b128 v[168:171], v172 offset:2048
	ds_read_b128 v[172:175], v172 offset:3072
	s_mov_b32 m0, s24
	v_lshl_add_u64 v[224:225], s[8:9], 0, v[128:129]
	ds_read_b128 v[176:179], v137 offset:32768
	ds_read_b128 v[180:183], v137 offset:33792
	ds_read_b128 v[184:187], v137 offset:34816
	ds_read_b128 v[188:191], v137 offset:35840
	ds_read_b128 v[192:195], v137 offset:36864
	ds_read_b128 v[196:199], v137 offset:37888
	ds_read_b128 v[210:213], v137 offset:38912
	ds_read_b128 v[214:217], v137 offset:39936
	global_load_lds_dwordx4 v[224:225], off
	v_lshl_add_u64 v[224:225], s[8:9], 0, v[130:131]
	s_mov_b32 m0, s25
	s_nop 0
	global_load_lds_dwordx4 v[224:225], off
	s_waitcnt vmcnt(8) lgkmcnt(0)
	s_barrier
	v_mfma_f32_16x16x32_bf16 v[124:127], v[138:141], v[176:179], v[124:127]
	v_mfma_f32_16x16x32_bf16 v[120:123], v[146:149], v[176:179], v[120:123]
	v_mfma_f32_16x16x32_bf16 v[116:119], v[138:141], v[184:187], v[116:119]
	v_mfma_f32_16x16x32_bf16 v[112:115], v[146:149], v[184:187], v[112:115]
	v_mfma_f32_16x16x32_bf16 v[100:103], v[138:141], v[192:195], v[100:103]
	v_mfma_f32_16x16x32_bf16 v[96:99], v[146:149], v[192:195], v[96:99]
	v_mfma_f32_16x16x32_bf16 v[84:87], v[138:141], v[210:213], v[84:87]
	v_mfma_f32_16x16x32_bf16 v[80:83], v[146:149], v[210:213], v[80:83]
	v_mfma_f32_16x16x32_bf16 v[124:127], v[142:145], v[180:183], v[124:127]
	v_mfma_f32_16x16x32_bf16 v[120:123], v[150:153], v[180:183], v[120:123]
	v_mfma_f32_16x16x32_bf16 v[116:119], v[142:145], v[188:191], v[116:119]
	v_mfma_f32_16x16x32_bf16 v[112:115], v[150:153], v[188:191], v[112:115]
	v_mfma_f32_16x16x32_bf16 v[100:103], v[142:145], v[196:199], v[100:103]
	v_mfma_f32_16x16x32_bf16 v[96:99], v[150:153], v[196:199], v[96:99]
	v_mfma_f32_16x16x32_bf16 v[84:87], v[142:145], v[214:217], v[84:87]
	v_mfma_f32_16x16x32_bf16 v[80:83], v[150:153], v[214:217], v[80:83]
	v_mfma_f32_16x16x32_bf16 v[108:111], v[154:157], v[176:179], v[108:111]
	v_mfma_f32_16x16x32_bf16 v[104:107], v[168:171], v[176:179], v[104:107]
	v_mfma_f32_16x16x32_bf16 v[92:95], v[154:157], v[184:187], v[92:95]
	v_mfma_f32_16x16x32_bf16 v[88:91], v[168:171], v[184:187], v[88:91]
	v_mfma_f32_16x16x32_bf16 v[76:79], v[154:157], v[192:195], v[76:79]
	v_mfma_f32_16x16x32_bf16 v[72:75], v[168:171], v[192:195], v[72:75]
	v_mfma_f32_16x16x32_bf16 v[68:71], v[154:157], v[210:213], v[68:71]
	v_mfma_f32_16x16x32_bf16 v[64:67], v[168:171], v[210:213], v[64:67]
	v_mfma_f32_16x16x32_bf16 v[108:111], v[162:165], v[180:183], v[108:111]
	v_mfma_f32_16x16x32_bf16 v[104:107], v[172:175], v[180:183], v[104:107]
	v_mfma_f32_16x16x32_bf16 v[92:95], v[162:165], v[188:191], v[92:95]
	v_mfma_f32_16x16x32_bf16 v[88:91], v[172:175], v[188:191], v[88:91]
	v_mfma_f32_16x16x32_bf16 v[76:79], v[162:165], v[196:199], v[76:79]
	v_mfma_f32_16x16x32_bf16 v[72:75], v[172:175], v[196:199], v[72:75]
	v_mfma_f32_16x16x32_bf16 v[68:71], v[162:165], v[214:217], v[68:71]
	v_mfma_f32_16x16x32_bf16 v[64:67], v[172:175], v[214:217], v[64:67]
	s_barrier
; #define PG8_STAGE(bufoff, gbase, voff) do { _Pragma("unroll") for (int _i = 0; _i < 2; ++_i) \
;         __builtin_amdgcn_global_load_lds((const unsigned*)((const char*)(gbase) + (voff)[_i]), (LAS unsigned*)(lds + (bufoff) + ldsw + _i * 8192), 16, 0, 0); } while (0)
; #define PG8_LDA(dst, b, h) do { _Pragma("unroll") for (int m = 0; m < 4; ++m) _Pragma("unroll") for (int k = 0; k < 2; ++k) dst[m][k] = *(const LAS bf16x8*)(lds + PG8_SA(b, h) + aoff + m * 2048 + k * 1024); } while (0)
; #define PG8_LDB(dst, b, h) do { _Pragma("unroll") for (int n = 0; n < 2; ++n) _Pragma("unroll") for (int k = 0; k < 2; ++k) dst[n][k] = *(const LAS bf16x8*)(lds + PG8_SB(b, h) + boff + n * 2048 + k * 1024); } while (0)
; #define PG8_MMA(ai, bj, At, Bt) do { __builtin_amdgcn_s_setprio(1); _Pragma("unroll") for (int m = 0; m < 4; ++m) _Pragma("unroll") for (int n = 0; n < 2; ++n) _Pragma("unroll") for (int k = 0; k < 2; ++k) \
;         acc[ai][bj][m][n] = __builtin_amdgcn_mfma_f32_16x16x32_bf16(Bt[n][k], At[m][k], acc[ai][bj][m][n], 0, 0, 0); __builtin_amdgcn_s_setprio(0); } while (0)
; #define PG8_WAIT_V(n) asm volatile("s_waitcnt vmcnt(" #n ")" ::: "memory")
; #define PG8_WAIT_L(n) asm volatile("s_waitcnt lgkmcnt(" #n ")" ::: "memory")
; #define PG8_BAR __builtin_amdgcn_s_barrier()
; #define PG8_SCHED __builtin_amdgcn_sched_barrier(0)
; template <class Epi, class Sched>
; DI void gemm_phase(const int wv, LAS unsigned char* lds, const int lda, const int ldb, const int K, const Sched& S, const Epi& E) {
;     ...
;             PG8_LDB(B0, 1, 0); PG8_LDB(B1, 1, 1); PG8_SCHED; PG8_LDA(At, 1, 0); PG8_STAGE(PG8_SA(0, 1), a2 + hstepA, voffA);
;             PG8_WAIT_V(8); PG8_WAIT_L(0); PG8_BAR; PG8_MMA(0, 0, At, B0); PG8_MMA(0, 1, At, B1); PG8_BAR; PG8_SCHED;
;             PG8_LDA(At, 1, 1); PG8_STAGE(PG8_SB(1, 0), b3, voffB); PG8_STAGE(PG8_SB(1, 1), b3 + hstepB, voffB); PG8_STAGE(PG8_SA(1, 0), a3, voffA);
;             PG8_WAIT_V(8); PG8_WAIT_L(0); PG8_BAR; PG8_MMA(1, 0, At, B0); PG8_MMA(1, 1, At, B1); PG8_BAR; PG8_SCHED;
;         }
;         if (wr == 0) PG8_BAR;
	s_mov_b32 m0, s30
	v_lshl_add_u64 v[158:159], v[158:159], 0, s[78:79]
	ds_read_b128 v[176:179], v137 offset:49152
	ds_read_b128 v[180:183], v137 offset:50176
	ds_read_b128 v[184:187], v137 offset:51200
	ds_read_b128 v[188:191], v137 offset:52224
	ds_read_b128 v[192:195], v137 offset:53248
	ds_read_b128 v[196:199], v137 offset:54272
	ds_read_b128 v[210:213], v137 offset:55296
	ds_read_b128 v[214:217], v137 offset:56320
	global_load_lds_dwordx4 v[158:159], off
	v_lshl_add_u64 v[158:159], v[218:219], 0, s[78:79]
	s_mov_b32 m0, s29
	s_nop 0
	global_load_lds_dwordx4 v[158:159], off
	v_lshl_add_u64 v[158:159], s[6:7], 0, v[160:161]
	s_mov_b32 m0, s40
	s_nop 0
	global_load_lds_dwordx4 v[158:159], off
	v_lshl_add_u64 v[158:159], s[6:7], 0, v[132:133]
	s_mov_b32 m0, s39
	s_nop 0
	global_load_lds_dwordx4 v[158:159], off
	v_lshl_add_u64 v[158:159], v[220:221], 0, s[78:79]
	s_mov_b32 m0, s27
	s_nop 0
	global_load_lds_dwordx4 v[158:159], off
	v_lshl_add_u64 v[158:159], v[222:223], 0, s[78:79]
	s_mov_b32 m0, s28
	s_nop 0
	global_load_lds_dwordx4 v[158:159], off
	s_waitcnt vmcnt(8) lgkmcnt(0)
	s_barrier
	v_mfma_f32_16x16x32_bf16 v[60:63], v[138:141], v[176:179], v[60:63]
	v_mfma_f32_16x16x32_bf16 v[56:59], v[146:149], v[176:179], v[56:59]
	v_mfma_f32_16x16x32_bf16 v[52:55], v[138:141], v[184:187], v[52:55]
	v_mfma_f32_16x16x32_bf16 v[48:51], v[146:149], v[184:187], v[48:51]
	v_mfma_f32_16x16x32_bf16 v[36:39], v[138:141], v[192:195], v[36:39]
	v_mfma_f32_16x16x32_bf16 v[32:35], v[146:149], v[192:195], v[32:35]
	v_mfma_f32_16x16x32_bf16 v[20:23], v[138:141], v[210:213], v[20:23]
	v_mfma_f32_16x16x32_bf16 v[16:19], v[146:149], v[210:213], v[16:19]
	v_mfma_f32_16x16x32_bf16 v[60:63], v[142:145], v[180:183], v[60:63]
	v_mfma_f32_16x16x32_bf16 v[56:59], v[150:153], v[180:183], v[56:59]
	v_mfma_f32_16x16x32_bf16 v[52:55], v[142:145], v[188:191], v[52:55]
	v_mfma_f32_16x16x32_bf16 v[48:51], v[150:153], v[188:191], v[48:51]
	v_mfma_f32_16x16x32_bf16 v[36:39], v[142:145], v[196:199], v[36:39]
	v_mfma_f32_16x16x32_bf16 v[32:35], v[150:153], v[196:199], v[32:35]
	v_mfma_f32_16x16x32_bf16 v[20:23], v[142:145], v[214:217], v[20:23]
	v_mfma_f32_16x16x32_bf16 v[16:19], v[150:153], v[214:217], v[16:19]
	v_mfma_f32_16x16x32_bf16 v[44:47], v[154:157], v[176:179], v[44:47]
	v_mfma_f32_16x16x32_bf16 v[40:43], v[168:171], v[176:179], v[40:43]
	v_mfma_f32_16x16x32_bf16 v[28:31], v[154:157], v[184:187], v[28:31]
	v_mfma_f32_16x16x32_bf16 v[24:27], v[168:171], v[184:187], v[24:27]
	v_mfma_f32_16x16x32_bf16 v[12:15], v[154:157], v[192:195], v[12:15]
	v_mfma_f32_16x16x32_bf16 v[8:11], v[168:171], v[192:195], v[8:11]
	v_mfma_f32_16x16x32_bf16 v[4:7], v[154:157], v[210:213], v[4:7]
	v_mfma_f32_16x16x32_bf16 v[0:3], v[168:171], v[210:213], v[0:3]
	v_mfma_f32_16x16x32_bf16 v[44:47], v[162:165], v[180:183], v[44:47]
	v_mfma_f32_16x16x32_bf16 v[40:43], v[172:175], v[180:183], v[40:43]
	v_mfma_f32_16x16x32_bf16 v[28:31], v[162:165], v[188:191], v[28:31]
	v_mfma_f32_16x16x32_bf16 v[24:27], v[172:175], v[188:191], v[24:27]
	v_mfma_f32_16x16x32_bf16 v[12:15], v[162:165], v[196:199], v[12:15]
	v_mfma_f32_16x16x32_bf16 v[8:11], v[172:175], v[196:199], v[8:11]
	v_mfma_f32_16x16x32_bf16 v[4:7], v[162:165], v[214:217], v[4:7]
	v_mfma_f32_16x16x32_bf16 v[0:3], v[172:175], v[214:217], v[0:3]
	s_barrier
	s_andn2_b64 vcc, exec, s[4:5]
	s_mov_b64 s[6:7], -1
	s_mov_b64 s[4:5], 0
	s_mov_b64 s[8:9], 0x100
	s_cbranch_vccz .LBB0_516
	s_cmpk_lt_u32 s20, 0x100
	s_cbranch_scc0 .LBB0_519
	s_barrier

; #define PG8_STAGE(bufoff, gbase, voff) do { _Pragma("unroll") for (int _i = 0; _i < 2; ++_i) \
;         __builtin_amdgcn_global_load_lds((const unsigned*)((const char*)(gbase) + (voff)[_i]), (LAS unsigned*)(lds + (bufoff) + ldsw + _i * 8192), 16, 0, 0); } while (0)
; #define PG8_LDA(dst, b, h) do { _Pragma("unroll") for (int m = 0; m < 4; ++m) _Pragma("unroll") for (int k = 0; k < 2; ++k) dst[m][k] = *(const LAS bf16x8*)(lds + PG8_SA(b, h) + aoff + m * 2048 + k * 1024); } while (0)
; #define PG8_LDB(dst, b, h) do { _Pragma("unroll") for (int n = 0; n < 2; ++n) _Pragma("unroll") for (int k = 0; k < 2; ++k) dst[n][k] = *(const LAS bf16x8*)(lds + PG8_SB(b, h) + boff + n * 2048 + k * 1024); } while (0)
; #define PG8_MMA(ai, bj, At, Bt) do { __builtin_amdgcn_s_setprio(1); _Pragma("unroll") for (int m = 0; m < 4; ++m) _Pragma("unroll") for (int n = 0; n < 2; ++n) _Pragma("unroll") for (int k = 0; k < 2; ++k) \
;         acc[ai][bj][m][n] = __builtin_amdgcn_mfma_f32_16x16x32_bf16(Bt[n][k], At[m][k], acc[ai][bj][m][n], 0, 0, 0); __builtin_amdgcn_s_setprio(0); } while (0)
; #define PG8_WAIT_V(n) asm volatile("s_waitcnt vmcnt(" #n ")" ::: "memory")
; #define PG8_WAIT_L(n) asm volatile("s_waitcnt lgkmcnt(" #n ")" ::: "memory")
; #define PG8_BAR __builtin_amdgcn_s_barrier()
; #define PG8_SCHED __builtin_amdgcn_sched_barrier(0)
; template <class Epi, class Sched>
; DI void gemm_phase(const int wv, LAS unsigned char* lds, const int lda, const int ldb, const int K, const Sched& S, const Epi& E) {
;     ...
;             const bool last = (t == nt - 2);
;             const char* a1 = cA + (size_t)(t + 1) * kstep;
;             const char* a2 = last ? nA : cA + (size_t)(t + 2) * kstep; const char* b2 = last ? nB : cB + (size_t)(t + 2) * kstep;
;             const char* a3 = a2 + kstep; const char* b3 = b2 + kstep;
;             PG8_LDB(B0, 0, 0); PG8_LDB(B1, 0, 1); PG8_SCHED; PG8_LDA(At, 0, 0); PG8_STAGE(PG8_SA(1, 1), a1 + hstepA, voffA);
;             PG8_WAIT_V(8); PG8_WAIT_L(0); PG8_BAR; PG8_MMA(0, 0, At, B0); PG8_MMA(0, 1, At, B1); PG8_BAR; PG8_SCHED;
;             PG8_LDA(At, 0, 1); PG8_STAGE(PG8_SB(0, 0), b2, voffB); PG8_STAGE(PG8_SB(0, 1), b2 + hstepB, voffB); PG8_STAGE(PG8_SA(0, 0), a2, voffA);
;             PG8_WAIT_V(8); PG8_WAIT_L(0); PG8_BAR; PG8_MMA(1, 0, At, B0); PG8_MMA(1, 1, At, B1); PG8_BAR; PG8_SCHED;
.LBB0_686:
	s_add_u32 s18, s16, 0xfff80080
	s_addc_u32 s19, s17, -1
	s_add_i32 s42, 0, 0x10000
	s_cmp_eq_u32 s41, 28
	s_cselect_b32 s21, s13, s19
	s_cselect_b32 s20, s12, s18
	s_cselect_b32 s19, s15, s40
	s_cselect_b32 s18, s14, s11
	s_add_i32 s44, 0, 0x14000
	v_add_u32_e32 v140, s42, v157
	v_add_u32_e32 v154, s44, v157
	ds_read_b128 v[128:131], v140
	ds_read_b128 v[132:135], v140 offset:1024
	ds_read_b128 v[136:139], v140 offset:2048
	ds_read_b128 v[140:143], v140 offset:3072
	ds_read_b128 v[162:165], v154
	ds_read_b128 v[168:171], v154 offset:1024
	ds_read_b128 v[172:175], v154 offset:2048
	ds_read_b128 v[176:179], v154 offset:3072
	v_lshl_add_u64 v[154:155], s[16:17], 0, v[152:153]
	s_add_i32 m0, s27, 0xc000
	ds_read_b128 v[180:183], v159
	ds_read_b128 v[184:187], v159 offset:1024
	ds_read_b128 v[188:191], v159 offset:2048
	ds_read_b128 v[192:195], v159 offset:3072
	ds_read_b128 v[196:199], v159 offset:4096
	ds_read_b128 v[210:213], v159 offset:5120
	ds_read_b128 v[214:217], v159 offset:6144
	ds_read_b128 v[218:221], v159 offset:7168
	global_load_lds_dwordx4 v[154:155], off
	v_lshl_add_u64 v[154:155], s[16:17], 0, v[150:151]
	s_add_i32 m0, s27, 0xe000
	s_nop 0
	global_load_lds_dwordx4 v[154:155], off
	s_waitcnt vmcnt(8) lgkmcnt(0)
	s_barrier
	v_mfma_f32_16x16x32_bf16 v[124:127], v[128:131], v[180:183], v[124:127]
	v_mfma_f32_16x16x32_bf16 v[120:123], v[136:139], v[180:183], v[120:123]
	v_mfma_f32_16x16x32_bf16 v[116:119], v[128:131], v[188:191], v[116:119]
	v_mfma_f32_16x16x32_bf16 v[108:111], v[136:139], v[188:191], v[108:111]
	v_mfma_f32_16x16x32_bf16 v[100:103], v[128:131], v[196:199], v[100:103]
	v_mfma_f32_16x16x32_bf16 v[92:95], v[136:139], v[196:199], v[92:95]
	v_mfma_f32_16x16x32_bf16 v[84:87], v[128:131], v[214:217], v[84:87]
	v_mfma_f32_16x16x32_bf16 v[76:79], v[136:139], v[214:217], v[76:79]
	v_mfma_f32_16x16x32_bf16 v[124:127], v[132:135], v[184:187], v[124:127]
	v_mfma_f32_16x16x32_bf16 v[120:123], v[140:143], v[184:187], v[120:123]
	v_mfma_f32_16x16x32_bf16 v[116:119], v[132:135], v[192:195], v[116:119]
	v_mfma_f32_16x16x32_bf16 v[108:111], v[140:143], v[192:195], v[108:111]
	v_mfma_f32_16x16x32_bf16 v[100:103], v[132:135], v[210:213], v[100:103]
	v_mfma_f32_16x16x32_bf16 v[92:95], v[140:143], v[210:213], v[92:95]
	v_mfma_f32_16x16x32_bf16 v[84:87], v[132:135], v[218:221], v[84:87]
	v_mfma_f32_16x16x32_bf16 v[76:79], v[140:143], v[218:221], v[76:79]
	v_mfma_f32_16x16x32_bf16 v[112:115], v[162:165], v[180:183], v[112:115]
	v_mfma_f32_16x16x32_bf16 v[104:107], v[172:175], v[180:183], v[104:107]
	v_mfma_f32_16x16x32_bf16 v[96:99], v[162:165], v[188:191], v[96:99]
	v_mfma_f32_16x16x32_bf16 v[88:91], v[172:175], v[188:191], v[88:91]
	v_mfma_f32_16x16x32_bf16 v[80:83], v[162:165], v[196:199], v[80:83]
	v_mfma_f32_16x16x32_bf16 v[72:75], v[172:175], v[196:199], v[72:75]
	v_mfma_f32_16x16x32_bf16 v[68:71], v[162:165], v[214:217], v[68:71]
	v_mfma_f32_16x16x32_bf16 v[64:67], v[172:175], v[214:217], v[64:67]
	v_mfma_f32_16x16x32_bf16 v[112:115], v[168:171], v[184:187], v[112:115]
	v_mfma_f32_16x16x32_bf16 v[104:107], v[176:179], v[184:187], v[104:107]
	v_mfma_f32_16x16x32_bf16 v[96:99], v[168:171], v[192:195], v[96:99]
	v_mfma_f32_16x16x32_bf16 v[88:91], v[176:179], v[192:195], v[88:91]
	v_mfma_f32_16x16x32_bf16 v[80:83], v[168:171], v[210:213], v[80:83]
	v_mfma_f32_16x16x32_bf16 v[72:75], v[176:179], v[210:213], v[72:75]
	v_mfma_f32_16x16x32_bf16 v[68:71], v[168:171], v[218:221], v[68:71]
	v_mfma_f32_16x16x32_bf16 v[64:67], v[176:179], v[218:221], v[64:67]
	s_barrier
	s_add_i32 s42, s42, s26
	v_lshl_add_u64 v[154:155], s[18:19], 0, v[160:161]
	s_mov_b32 m0, s42
	ds_read_b128 v[180:183], v159 offset:16384
	ds_read_b128 v[184:187], v159 offset:17408
	ds_read_b128 v[188:191], v159 offset:18432
	ds_read_b128 v[192:195], v159 offset:19456
	ds_read_b128 v[196:199], v159 offset:20480
	ds_read_b128 v[210:213], v159 offset:21504
	ds_read_b128 v[214:217], v159 offset:22528
	ds_read_b128 v[218:221], v159 offset:23552
	global_load_lds_dwordx4 v[154:155], off
	s_add_i32 m0, s42, 0x2000
	s_add_u32 s42, s18, 0x80000
	v_lshl_add_u64 v[222:223], s[18:19], 0, v[144:145]
	s_addc_u32 s43, s19, 0
	s_add_i32 s44, s44, s26
	global_load_lds_dwordx4 v[222:223], off
	v_lshl_add_u64 v[224:225], s[42:43], 0, v[160:161]
	s_mov_b32 m0, s44
	v_lshl_add_u64 v[226:227], s[20:21], 0, v[146:147]
	global_load_lds_dwordx4 v[224:225], off
	v_lshl_add_u64 v[224:225], s[42:43], 0, v[144:145]
	s_add_i32 m0, s44, 0x2000
	s_nop 0
	global_load_lds_dwordx4 v[224:225], off
	v_lshl_add_u64 v[224:225], s[20:21], 0, v[148:149]
	s_mov_b32 m0, s27
	s_nop 0
	global_load_lds_dwordx4 v[224:225], off
	s_mov_b32 m0, s28
	s_nop 0
	global_load_lds_dwordx4 v[226:227], off
	s_waitcnt vmcnt(8) lgkmcnt(0)
	s_barrier
; #define PG8_STAGE(bufoff, gbase, voff) do { _Pragma("unroll") for (int _i = 0; _i < 2; ++_i) \
;         __builtin_amdgcn_global_load_lds((const unsigned*)((const char*)(gbase) + (voff)[_i]), (LAS unsigned*)(lds + (bufoff) + ldsw + _i * 8192), 16, 0, 0); } while (0)
; #define PG8_LDA(dst, b, h) do { _Pragma("unroll") for (int m = 0; m < 4; ++m) _Pragma("unroll") for (int k = 0; k < 2; ++k) dst[m][k] = *(const LAS bf16x8*)(lds + PG8_SA(b, h) + aoff + m * 2048 + k * 1024); } while (0)
; #define PG8_LDB(dst, b, h) do { _Pragma("unroll") for (int n = 0; n < 2; ++n) _Pragma("unroll") for (int k = 0; k < 2; ++k) dst[n][k] = *(const LAS bf16x8*)(lds + PG8_SB(b, h) + boff + n * 2048 + k * 1024); } while (0)
; #define PG8_MMA(ai, bj, At, Bt) do { __builtin_amdgcn_s_setprio(1); _Pragma("unroll") for (int m = 0; m < 4; ++m) _Pragma("unroll") for (int n = 0; n < 2; ++n) _Pragma("unroll") for (int k = 0; k < 2; ++k) \
;         acc[ai][bj][m][n] = __builtin_amdgcn_mfma_f32_16x16x32_bf16(Bt[n][k], At[m][k], acc[ai][bj][m][n], 0, 0, 0); __builtin_amdgcn_s_setprio(0); } while (0)
; #define PG8_WAIT_V(n) asm volatile("s_waitcnt vmcnt(" #n ")" ::: "memory")
; #define PG8_WAIT_L(n) asm volatile("s_waitcnt lgkmcnt(" #n ")" ::: "memory")
; #define PG8_BAR __builtin_amdgcn_s_barrier()
; #define PG8_SCHED __builtin_amdgcn_sched_barrier(0)
; template <class Epi, class Sched>
; DI void gemm_phase(const int wv, LAS unsigned char* lds, const int lda, const int ldb, const int K, const Sched& S, const Epi& E) {
;     ...
;             PG8_WAIT_V(8); PG8_WAIT_L(0); PG8_BAR; PG8_MMA(1, 0, At, B0); PG8_MMA(1, 1, At, B1); PG8_BAR; PG8_SCHED;
;             PG8_LDB(B0, 1, 0); PG8_LDB(B1, 1, 1); PG8_SCHED; PG8_LDA(At, 1, 0); PG8_STAGE(PG8_SA(0, 1), a2 + hstepA, voffA);
;             PG8_WAIT_V(8); PG8_WAIT_L(0); PG8_BAR; PG8_MMA(0, 0, At, B0); PG8_MMA(0, 1, At, B1); PG8_BAR; PG8_SCHED;
;             PG8_LDA(At, 1, 1); PG8_STAGE(PG8_SB(1, 0), b3, voffB); PG8_STAGE(PG8_SB(1, 1), b3 + hstepB, voffB); PG8_STAGE(PG8_SA(1, 0), a3, voffA);
;             PG8_WAIT_V(8); PG8_WAIT_L(0); PG8_BAR; PG8_MMA(1, 0, At, B0); PG8_MMA(1, 1, At, B1); PG8_BAR; PG8_SCHED;
	v_mfma_f32_16x16x32_bf16 v[60:63], v[128:131], v[180:183], v[60:63]
	v_mfma_f32_16x16x32_bf16 v[56:59], v[136:139], v[180:183], v[56:59]
	v_mfma_f32_16x16x32_bf16 v[52:55], v[128:131], v[188:191], v[52:55]
	v_mfma_f32_16x16x32_bf16 v[44:47], v[136:139], v[188:191], v[44:47]
	v_mfma_f32_16x16x32_bf16 v[36:39], v[128:131], v[196:199], v[36:39]
	v_mfma_f32_16x16x32_bf16 v[28:31], v[136:139], v[196:199], v[28:31]
	v_mfma_f32_16x16x32_bf16 v[20:23], v[128:131], v[214:217], v[20:23]
	v_mfma_f32_16x16x32_bf16 v[12:15], v[136:139], v[214:217], v[12:15]
	v_mfma_f32_16x16x32_bf16 v[60:63], v[132:135], v[184:187], v[60:63]
	v_mfma_f32_16x16x32_bf16 v[56:59], v[140:143], v[184:187], v[56:59]
	v_mfma_f32_16x16x32_bf16 v[52:55], v[132:135], v[192:195], v[52:55]
	v_mfma_f32_16x16x32_bf16 v[44:47], v[140:143], v[192:195], v[44:47]
	v_mfma_f32_16x16x32_bf16 v[36:39], v[132:135], v[210:213], v[36:39]
	v_mfma_f32_16x16x32_bf16 v[28:31], v[140:143], v[210:213], v[28:31]
	v_mfma_f32_16x16x32_bf16 v[20:23], v[132:135], v[218:221], v[20:23]
	v_mfma_f32_16x16x32_bf16 v[12:15], v[140:143], v[218:221], v[12:15]
	v_mfma_f32_16x16x32_bf16 v[48:51], v[162:165], v[180:183], v[48:51]
	v_mfma_f32_16x16x32_bf16 v[40:43], v[172:175], v[180:183], v[40:43]
	v_mfma_f32_16x16x32_bf16 v[32:35], v[162:165], v[188:191], v[32:35]
	v_mfma_f32_16x16x32_bf16 v[24:27], v[172:175], v[188:191], v[24:27]
	v_mfma_f32_16x16x32_bf16 v[16:19], v[162:165], v[196:199], v[16:19]
	v_mfma_f32_16x16x32_bf16 v[8:11], v[172:175], v[196:199], v[8:11]
	v_mfma_f32_16x16x32_bf16 v[4:7], v[162:165], v[214:217], v[4:7]
	v_mfma_f32_16x16x32_bf16 v[0:3], v[172:175], v[214:217], v[0:3]
	v_mfma_f32_16x16x32_bf16 v[48:51], v[168:171], v[184:187], v[48:51]
	v_mfma_f32_16x16x32_bf16 v[40:43], v[176:179], v[184:187], v[40:43]
	v_mfma_f32_16x16x32_bf16 v[32:35], v[168:171], v[192:195], v[32:35]
	v_mfma_f32_16x16x32_bf16 v[24:27], v[176:179], v[192:195], v[24:27]
	v_mfma_f32_16x16x32_bf16 v[16:19], v[168:171], v[210:213], v[16:19]
	v_mfma_f32_16x16x32_bf16 v[8:11], v[176:179], v[210:213], v[8:11]
	v_mfma_f32_16x16x32_bf16 v[4:7], v[168:171], v[218:221], v[4:7]
	v_mfma_f32_16x16x32_bf16 v[0:3], v[176:179], v[218:221], v[0:3]
	s_barrier
	s_add_i32 s42, 0, 0x18000
	s_add_i32 s43, 0, 0x1c000
	v_add_u32_e32 v140, s42, v157
	v_add_u32_e32 v176, s43, v157
	ds_read_b128 v[128:131], v140
	ds_read_b128 v[132:135], v140 offset:1024
	ds_read_b128 v[136:139], v140 offset:2048
	ds_read_b128 v[140:143], v140 offset:3072
	ds_read_b128 v[162:165], v176
	ds_read_b128 v[168:171], v176 offset:1024
	ds_read_b128 v[172:175], v176 offset:2048
	ds_read_b128 v[176:179], v176 offset:3072
	s_add_u32 s20, s20, 0x80000
	s_addc_u32 s21, s21, 0
	s_mov_b32 m0, s29
	v_lshl_add_u64 v[228:229], s[20:21], 0, v[148:149]
	ds_read_b128 v[180:183], v159 offset:32768
	ds_read_b128 v[184:187], v159 offset:33792
	ds_read_b128 v[188:191], v159 offset:34816
	ds_read_b128 v[192:195], v159 offset:35840
	ds_read_b128 v[196:199], v159 offset:36864
	ds_read_b128 v[210:213], v159 offset:37888
	ds_read_b128 v[214:217], v159 offset:38912
	ds_read_b128 v[218:221], v159 offset:39936
	global_load_lds_dwordx4 v[228:229], off
	v_lshl_add_u64 v[228:229], s[20:21], 0, v[146:147]
	s_mov_b32 m0, s30
	s_nop 0
	global_load_lds_dwordx4 v[228:229], off
	s_waitcnt vmcnt(8) lgkmcnt(0)
	s_barrier
	v_mfma_f32_16x16x32_bf16 v[124:127], v[128:131], v[180:183], v[124:127]
	v_mfma_f32_16x16x32_bf16 v[120:123], v[136:139], v[180:183], v[120:123]
	v_mfma_f32_16x16x32_bf16 v[116:119], v[128:131], v[188:191], v[116:119]
	v_mfma_f32_16x16x32_bf16 v[108:111], v[136:139], v[188:191], v[108:111]
	v_mfma_f32_16x16x32_bf16 v[100:103], v[128:131], v[196:199], v[100:103]
	v_mfma_f32_16x16x32_bf16 v[92:95], v[136:139], v[196:199], v[92:95]
	v_mfma_f32_16x16x32_bf16 v[84:87], v[128:131], v[214:217], v[84:87]
	v_mfma_f32_16x16x32_bf16 v[76:79], v[136:139], v[214:217], v[76:79]
	v_mfma_f32_16x16x32_bf16 v[124:127], v[132:135], v[184:187], v[124:127]
	v_mfma_f32_16x16x32_bf16 v[120:123], v[140:143], v[184:187], v[120:123]
	v_mfma_f32_16x16x32_bf16 v[116:119], v[132:135], v[192:195], v[116:119]
	v_mfma_f32_16x16x32_bf16 v[108:111], v[140:143], v[192:195], v[108:111]
	v_mfma_f32_16x16x32_bf16 v[100:103], v[132:135], v[210:213], v[100:103]
	v_mfma_f32_16x16x32_bf16 v[92:95], v[140:143], v[210:213], v[92:95]
	v_mfma_f32_16x16x32_bf16 v[84:87], v[132:135], v[218:221], v[84:87]
	v_mfma_f32_16x16x32_bf16 v[76:79], v[140:143], v[218:221], v[76:79]
	v_mfma_f32_16x16x32_bf16 v[112:115], v[162:165], v[180:183], v[112:115]
	v_mfma_f32_16x16x32_bf16 v[104:107], v[172:175], v[180:183], v[104:107]
	v_mfma_f32_16x16x32_bf16 v[96:99], v[162:165], v[188:191], v[96:99]
	v_mfma_f32_16x16x32_bf16 v[88:91], v[172:175], v[188:191], v[88:91]
	v_mfma_f32_16x16x32_bf16 v[80:83], v[162:165], v[196:199], v[80:83]
	v_mfma_f32_16x16x32_bf16 v[72:75], v[172:175], v[196:199], v[72:75]
	v_mfma_f32_16x16x32_bf16 v[68:71], v[162:165], v[214:217], v[68:71]
	v_mfma_f32_16x16x32_bf16 v[64:67], v[172:175], v[214:217], v[64:67]
	v_mfma_f32_16x16x32_bf16 v[112:115], v[168:171], v[184:187], v[112:115]
	v_mfma_f32_16x16x32_bf16 v[104:107], v[176:179], v[184:187], v[104:107]
	v_mfma_f32_16x16x32_bf16 v[96:99], v[168:171], v[192:195], v[96:99]
	v_mfma_f32_16x16x32_bf16 v[88:91], v[176:179], v[192:195], v[88:91]
	v_mfma_f32_16x16x32_bf16 v[80:83], v[168:171], v[210:213], v[80:83]
	v_mfma_f32_16x16x32_bf16 v[72:75], v[176:179], v[210:213], v[72:75]
	v_mfma_f32_16x16x32_bf16 v[68:71], v[168:171], v[218:221], v[68:71]
	v_mfma_f32_16x16x32_bf16 v[64:67], v[176:179], v[218:221], v[64:67]
	s_barrier
; #define PG8_STAGE(bufoff, gbase, voff) do { _Pragma("unroll") for (int _i = 0; _i < 2; ++_i) \
;         __builtin_amdgcn_global_load_lds((const unsigned*)((const char*)(gbase) + (voff)[_i]), (LAS unsigned*)(lds + (bufoff) + ldsw + _i * 8192), 16, 0, 0); } while (0)
; #define PG8_LDA(dst, b, h) do { _Pragma("unroll") for (int m = 0; m < 4; ++m) _Pragma("unroll") for (int k = 0; k < 2; ++k) dst[m][k] = *(const LAS bf16x8*)(lds + PG8_SA(b, h) + aoff + m * 2048 + k * 1024); } while (0)
; #define PG8_LDB(dst, b, h) do { _Pragma("unroll") for (int n = 0; n < 2; ++n) _Pragma("unroll") for (int k = 0; k < 2; ++k) dst[n][k] = *(const LAS bf16x8*)(lds + PG8_SB(b, h) + boff + n * 2048 + k * 1024); } while (0)
; #define PG8_MMA(ai, bj, At, Bt) do { __builtin_amdgcn_s_setprio(1); _Pragma("unroll") for (int m = 0; m < 4; ++m) _Pragma("unroll") for (int n = 0; n < 2; ++n) _Pragma("unroll") for (int k = 0; k < 2; ++k) \
;         acc[ai][bj][m][n] = __builtin_amdgcn_mfma_f32_16x16x32_bf16(Bt[n][k], At[m][k], acc[ai][bj][m][n], 0, 0, 0); __builtin_amdgcn_s_setprio(0); } while (0)
; #define PG8_WAIT_V(n) asm volatile("s_waitcnt vmcnt(" #n ")" ::: "memory")
; #define PG8_WAIT_L(n) asm volatile("s_waitcnt lgkmcnt(" #n ")" ::: "memory")
; #define PG8_BAR __builtin_amdgcn_s_barrier()
; #define PG8_SCHED __builtin_amdgcn_sched_barrier(0)
; template <class Epi, class Sched>
; DI void gemm_phase(const int wv, LAS unsigned char* lds, const int lda, const int ldb, const int K, const Sched& S, const Epi& E) {
;     ...
;             PG8_LDB(B0, 1, 0); PG8_LDB(B1, 1, 1); PG8_SCHED; PG8_LDA(At, 1, 0); PG8_STAGE(PG8_SA(0, 1), a2 + hstepA, voffA);
;             PG8_WAIT_V(8); PG8_WAIT_L(0); PG8_BAR; PG8_MMA(0, 0, At, B0); PG8_MMA(0, 1, At, B1); PG8_BAR; PG8_SCHED;
;             PG8_LDA(At, 1, 1); PG8_STAGE(PG8_SB(1, 0), b3, voffB); PG8_STAGE(PG8_SB(1, 1), b3 + hstepB, voffB); PG8_STAGE(PG8_SA(1, 0), a3, voffA);
;             PG8_WAIT_V(8); PG8_WAIT_L(0); PG8_BAR; PG8_MMA(1, 0, At, B0); PG8_MMA(1, 1, At, B1); PG8_BAR; PG8_SCHED;
;         }
;         if (wr == 0) PG8_BAR;
	s_add_i32 s20, s42, s26
	v_lshl_add_u64 v[154:155], v[154:155], 0, s[78:79]
	s_mov_b32 m0, s20
	ds_read_b128 v[180:183], v159 offset:49152
	ds_read_b128 v[184:187], v159 offset:50176
	ds_read_b128 v[188:191], v159 offset:51200
	ds_read_b128 v[192:195], v159 offset:52224
	ds_read_b128 v[196:199], v159 offset:53248
	ds_read_b128 v[210:213], v159 offset:54272
	ds_read_b128 v[214:217], v159 offset:55296
	ds_read_b128 v[218:221], v159 offset:56320
	global_load_lds_dwordx4 v[154:155], off
	s_add_i32 m0, s20, 0x2000
	s_add_u32 s18, s18, 0x80080
	v_lshl_add_u64 v[154:155], v[222:223], 0, s[78:79]
	s_addc_u32 s19, s19, 0
	s_add_i32 s20, s43, s26
	global_load_lds_dwordx4 v[154:155], off
	v_lshl_add_u64 v[154:155], s[18:19], 0, v[160:161]
	s_mov_b32 m0, s20
	s_nop 0
	global_load_lds_dwordx4 v[154:155], off
	v_lshl_add_u64 v[154:155], s[18:19], 0, v[144:145]
	s_add_i32 m0, s20, 0x2000
	s_nop 0
	global_load_lds_dwordx4 v[154:155], off
	v_lshl_add_u64 v[154:155], v[224:225], 0, s[78:79]
	s_mov_b32 m0, s35
	s_nop 0
	global_load_lds_dwordx4 v[154:155], off
	v_lshl_add_u64 v[154:155], v[226:227], 0, s[78:79]
	s_mov_b32 m0, s36
	s_nop 0
	global_load_lds_dwordx4 v[154:155], off
	s_waitcnt vmcnt(8) lgkmcnt(0)
	s_barrier
	v_mfma_f32_16x16x32_bf16 v[60:63], v[128:131], v[180:183], v[60:63]
	v_mfma_f32_16x16x32_bf16 v[56:59], v[136:139], v[180:183], v[56:59]
	v_mfma_f32_16x16x32_bf16 v[52:55], v[128:131], v[188:191], v[52:55]
	v_mfma_f32_16x16x32_bf16 v[44:47], v[136:139], v[188:191], v[44:47]
	v_mfma_f32_16x16x32_bf16 v[36:39], v[128:131], v[196:199], v[36:39]
	v_mfma_f32_16x16x32_bf16 v[28:31], v[136:139], v[196:199], v[28:31]
	v_mfma_f32_16x16x32_bf16 v[20:23], v[128:131], v[214:217], v[20:23]
	v_mfma_f32_16x16x32_bf16 v[12:15], v[136:139], v[214:217], v[12:15]
	v_mfma_f32_16x16x32_bf16 v[60:63], v[132:135], v[184:187], v[60:63]
	v_mfma_f32_16x16x32_bf16 v[56:59], v[140:143], v[184:187], v[56:59]
	v_mfma_f32_16x16x32_bf16 v[52:55], v[132:135], v[192:195], v[52:55]
	v_mfma_f32_16x16x32_bf16 v[44:47], v[140:143], v[192:195], v[44:47]
	v_mfma_f32_16x16x32_bf16 v[36:39], v[132:135], v[210:213], v[36:39]
	v_mfma_f32_16x16x32_bf16 v[28:31], v[140:143], v[210:213], v[28:31]
	v_mfma_f32_16x16x32_bf16 v[20:23], v[132:135], v[218:221], v[20:23]
	v_mfma_f32_16x16x32_bf16 v[12:15], v[140:143], v[218:221], v[12:15]
	v_mfma_f32_16x16x32_bf16 v[48:51], v[162:165], v[180:183], v[48:51]
	v_mfma_f32_16x16x32_bf16 v[40:43], v[172:175], v[180:183], v[40:43]
	v_mfma_f32_16x16x32_bf16 v[32:35], v[162:165], v[188:191], v[32:35]
	v_mfma_f32_16x16x32_bf16 v[24:27], v[172:175], v[188:191], v[24:27]
	v_mfma_f32_16x16x32_bf16 v[16:19], v[162:165], v[196:199], v[16:19]
	v_mfma_f32_16x16x32_bf16 v[8:11], v[172:175], v[196:199], v[8:11]
	v_mfma_f32_16x16x32_bf16 v[4:7], v[162:165], v[214:217], v[4:7]
	v_mfma_f32_16x16x32_bf16 v[0:3], v[172:175], v[214:217], v[0:3]
	v_mfma_f32_16x16x32_bf16 v[48:51], v[168:171], v[184:187], v[48:51]
	v_mfma_f32_16x16x32_bf16 v[40:43], v[176:179], v[184:187], v[40:43]
	v_mfma_f32_16x16x32_bf16 v[32:35], v[168:171], v[192:195], v[32:35]
	v_mfma_f32_16x16x32_bf16 v[24:27], v[176:179], v[192:195], v[24:27]
	v_mfma_f32_16x16x32_bf16 v[16:19], v[168:171], v[210:213], v[16:19]
	v_mfma_f32_16x16x32_bf16 v[8:11], v[176:179], v[210:213], v[8:11]
	v_mfma_f32_16x16x32_bf16 v[4:7], v[168:171], v[218:221], v[4:7]
	v_mfma_f32_16x16x32_bf16 v[0:3], v[176:179], v[218:221], v[0:3]
	s_barrier
	s_add_i32 s41, s41, 2
	s_add_u32 s11, s11, 0x100
	s_addc_u32 s40, s40, 0
	s_add_u32 s16, s16, 0x100
	s_addc_u32 s17, s17, 0
	s_cmp_gt_u32 s41, 29
	s_cbranch_scc0 .LBB0_686
	s_and_b64 vcc, exec, s[8:9]
	s_cbranch_vccz .LBB0_689
	s_barrier

; #define PG8_STAGE(bufoff, gbase, voff) do { _Pragma("unroll") for (int _i = 0; _i < 2; ++_i) \
;         __builtin_amdgcn_global_load_lds((const unsigned*)((const char*)(gbase) + (voff)[_i]), (LAS unsigned*)(lds + (bufoff) + ldsw + _i * 8192), 16, 0, 0); } while (0)
; #define PG8_LDA(dst, b, h) do { _Pragma("unroll") for (int m = 0; m < 4; ++m) _Pragma("unroll") for (int k = 0; k < 2; ++k) dst[m][k] = *(const LAS bf16x8*)(lds + PG8_SA(b, h) + aoff + m * 2048 + k * 1024); } while (0)
; #define PG8_LDB(dst, b, h) do { _Pragma("unroll") for (int n = 0; n < 2; ++n) _Pragma("unroll") for (int k = 0; k < 2; ++k) dst[n][k] = *(const LAS bf16x8*)(lds + PG8_SB(b, h) + boff + n * 2048 + k * 1024); } while (0)
; #define PG8_MMA(ai, bj, At, Bt) do { __builtin_amdgcn_s_setprio(1); _Pragma("unroll") for (int m = 0; m < 4; ++m) _Pragma("unroll") for (int n = 0; n < 2; ++n) _Pragma("unroll") for (int k = 0; k < 2; ++k) \
;         acc[ai][bj][m][n] = __builtin_amdgcn_mfma_f32_16x16x32_bf16(Bt[n][k], At[m][k], acc[ai][bj][m][n], 0, 0, 0); __builtin_amdgcn_s_setprio(0); } while (0)
; #define PG8_WAIT_V(n) asm volatile("s_waitcnt vmcnt(" #n ")" ::: "memory")
; #define PG8_WAIT_L(n) asm volatile("s_waitcnt lgkmcnt(" #n ")" ::: "memory")
; #define PG8_BAR __builtin_amdgcn_s_barrier()
; #define PG8_SCHED __builtin_amdgcn_sched_barrier(0)
; template <class Epi, class Sched>
; DI void gemm_phase(const int wv, LAS unsigned char* lds, const int lda, const int ldb, const int K, const Sched& S, const Epi& E) {
;     ...
;             const bool last = (t == nt - 2);
;             const char* a1 = cA + (size_t)(t + 1) * kstep;
;             const char* a2 = last ? nA : cA + (size_t)(t + 2) * kstep; const char* b2 = last ? nB : cB + (size_t)(t + 2) * kstep;
;             const char* a3 = a2 + kstep; const char* b3 = b2 + kstep;
;             PG8_LDB(B0, 0, 0); PG8_LDB(B1, 0, 1); PG8_SCHED; PG8_LDA(At, 0, 0); PG8_STAGE(PG8_SA(1, 1), a1 + hstepA, voffA);
;             PG8_WAIT_V(8); PG8_WAIT_L(0); PG8_BAR; PG8_MMA(0, 0, At, B0); PG8_MMA(0, 1, At, B1); PG8_BAR; PG8_SCHED;
;             PG8_LDA(At, 0, 1); PG8_STAGE(PG8_SB(0, 0), b2, voffB); PG8_STAGE(PG8_SB(0, 1), b2 + hstepB, voffB); PG8_STAGE(PG8_SA(0, 0), a2, voffA);
;             PG8_WAIT_V(8); PG8_WAIT_L(0); PG8_BAR; PG8_MMA(1, 0, At, B0); PG8_MMA(1, 1, At, B1); PG8_BAR; PG8_SCHED;
.LBB0_825:
	s_add_u32 s20, s18, 0xfff80080
	s_addc_u32 s21, s19, -1
	s_add_i32 s42, 0, 0x10000
	s_cmp_eq_u32 s41, 28
	s_cselect_b32 s23, s15, s21
	s_cselect_b32 s22, s14, s20
	s_cselect_b32 s21, s17, s40
	s_cselect_b32 s20, s16, s13
	s_add_i32 s44, 0, 0x14000
	v_add_u32_e32 v154, s42, v139
	v_add_u32_e32 v158, s44, v139
	ds_read_b128 v[142:145], v154
	ds_read_b128 v[146:149], v154 offset:1024
	ds_read_b128 v[150:153], v154 offset:2048
	ds_read_b128 v[154:157], v154 offset:3072
	ds_read_b128 v[162:165], v158
	ds_read_b128 v[168:171], v158 offset:1024
	ds_read_b128 v[172:175], v158 offset:2048
	ds_read_b128 v[176:179], v158 offset:3072
	v_lshl_add_u64 v[158:159], s[18:19], 0, v[136:137]
	s_add_i32 m0, s29, 0xc000
	ds_read_b128 v[180:183], v141
	ds_read_b128 v[184:187], v141 offset:1024
	ds_read_b128 v[188:191], v141 offset:2048
	ds_read_b128 v[192:195], v141 offset:3072
	ds_read_b128 v[196:199], v141 offset:4096
	ds_read_b128 v[210:213], v141 offset:5120
	ds_read_b128 v[214:217], v141 offset:6144
	ds_read_b128 v[218:221], v141 offset:7168
	global_load_lds_dwordx4 v[158:159], off
	v_lshl_add_u64 v[158:159], s[18:19], 0, v[134:135]
	s_add_i32 m0, s29, 0xe000
	s_nop 0
	global_load_lds_dwordx4 v[158:159], off
	s_waitcnt vmcnt(8) lgkmcnt(0)
	s_barrier
	v_mfma_f32_16x16x32_bf16 v[124:127], v[142:145], v[180:183], v[124:127]
	v_mfma_f32_16x16x32_bf16 v[120:123], v[150:153], v[180:183], v[120:123]
	v_mfma_f32_16x16x32_bf16 v[108:111], v[142:145], v[188:191], v[108:111]
	v_mfma_f32_16x16x32_bf16 v[104:107], v[150:153], v[188:191], v[104:107]
	v_mfma_f32_16x16x32_bf16 v[92:95], v[142:145], v[196:199], v[92:95]
	v_mfma_f32_16x16x32_bf16 v[88:91], v[150:153], v[196:199], v[88:91]
	v_mfma_f32_16x16x32_bf16 v[76:79], v[142:145], v[214:217], v[76:79]
	v_mfma_f32_16x16x32_bf16 v[72:75], v[150:153], v[214:217], v[72:75]
	v_mfma_f32_16x16x32_bf16 v[124:127], v[146:149], v[184:187], v[124:127]
	v_mfma_f32_16x16x32_bf16 v[120:123], v[154:157], v[184:187], v[120:123]
	v_mfma_f32_16x16x32_bf16 v[108:111], v[146:149], v[192:195], v[108:111]
	v_mfma_f32_16x16x32_bf16 v[104:107], v[154:157], v[192:195], v[104:107]
	v_mfma_f32_16x16x32_bf16 v[92:95], v[146:149], v[210:213], v[92:95]
	v_mfma_f32_16x16x32_bf16 v[88:91], v[154:157], v[210:213], v[88:91]
	v_mfma_f32_16x16x32_bf16 v[76:79], v[146:149], v[218:221], v[76:79]
	v_mfma_f32_16x16x32_bf16 v[72:75], v[154:157], v[218:221], v[72:75]
	v_mfma_f32_16x16x32_bf16 v[116:119], v[162:165], v[180:183], v[116:119]
	v_mfma_f32_16x16x32_bf16 v[112:115], v[172:175], v[180:183], v[112:115]
	v_mfma_f32_16x16x32_bf16 v[100:103], v[162:165], v[188:191], v[100:103]
	v_mfma_f32_16x16x32_bf16 v[96:99], v[172:175], v[188:191], v[96:99]
	v_mfma_f32_16x16x32_bf16 v[84:87], v[162:165], v[196:199], v[84:87]
	v_mfma_f32_16x16x32_bf16 v[80:83], v[172:175], v[196:199], v[80:83]
	v_mfma_f32_16x16x32_bf16 v[68:71], v[162:165], v[214:217], v[68:71]
	v_mfma_f32_16x16x32_bf16 v[64:67], v[172:175], v[214:217], v[64:67]
	v_mfma_f32_16x16x32_bf16 v[116:119], v[168:171], v[184:187], v[116:119]
	v_mfma_f32_16x16x32_bf16 v[112:115], v[176:179], v[184:187], v[112:115]
	v_mfma_f32_16x16x32_bf16 v[100:103], v[168:171], v[192:195], v[100:103]
	v_mfma_f32_16x16x32_bf16 v[96:99], v[176:179], v[192:195], v[96:99]
	v_mfma_f32_16x16x32_bf16 v[84:87], v[168:171], v[210:213], v[84:87]
	v_mfma_f32_16x16x32_bf16 v[80:83], v[176:179], v[210:213], v[80:83]
	v_mfma_f32_16x16x32_bf16 v[68:71], v[168:171], v[218:221], v[68:71]
	v_mfma_f32_16x16x32_bf16 v[64:67], v[176:179], v[218:221], v[64:67]
	s_barrier
	s_add_i32 s42, s42, s28
	v_lshl_add_u64 v[158:159], s[20:21], 0, v[160:161]
	s_mov_b32 m0, s42
	ds_read_b128 v[180:183], v141 offset:16384
	ds_read_b128 v[184:187], v141 offset:17408
	ds_read_b128 v[188:191], v141 offset:18432
	ds_read_b128 v[192:195], v141 offset:19456
	ds_read_b128 v[196:199], v141 offset:20480
	ds_read_b128 v[210:213], v141 offset:21504
	ds_read_b128 v[214:217], v141 offset:22528
	ds_read_b128 v[218:221], v141 offset:23552
	global_load_lds_dwordx4 v[158:159], off
	s_add_i32 m0, s42, 0x2000
	s_add_u32 s42, s20, 0x80000
	v_lshl_add_u64 v[222:223], s[20:21], 0, v[128:129]
	s_addc_u32 s43, s21, 0
	s_add_i32 s44, s44, s28
	global_load_lds_dwordx4 v[222:223], off
	v_lshl_add_u64 v[224:225], s[42:43], 0, v[160:161]
	s_mov_b32 m0, s44
	v_lshl_add_u64 v[226:227], s[22:23], 0, v[130:131]
	global_load_lds_dwordx4 v[224:225], off
	v_lshl_add_u64 v[224:225], s[42:43], 0, v[128:129]
	s_add_i32 m0, s44, 0x2000
	s_nop 0
	global_load_lds_dwordx4 v[224:225], off
	v_lshl_add_u64 v[224:225], s[22:23], 0, v[132:133]
	s_mov_b32 m0, s29
	s_nop 0
	global_load_lds_dwordx4 v[224:225], off
	s_mov_b32 m0, s30
	s_nop 0
	global_load_lds_dwordx4 v[226:227], off
	s_waitcnt vmcnt(8) lgkmcnt(0)
	s_barrier
; #define PG8_STAGE(bufoff, gbase, voff) do { _Pragma("unroll") for (int _i = 0; _i < 2; ++_i) \
;         __builtin_amdgcn_global_load_lds((const unsigned*)((const char*)(gbase) + (voff)[_i]), (LAS unsigned*)(lds + (bufoff) + ldsw + _i * 8192), 16, 0, 0); } while (0)
; #define PG8_LDA(dst, b, h) do { _Pragma("unroll") for (int m = 0; m < 4; ++m) _Pragma("unroll") for (int k = 0; k < 2; ++k) dst[m][k] = *(const LAS bf16x8*)(lds + PG8_SA(b, h) + aoff + m * 2048 + k * 1024); } while (0)
; #define PG8_LDB(dst, b, h) do { _Pragma("unroll") for (int n = 0; n < 2; ++n) _Pragma("unroll") for (int k = 0; k < 2; ++k) dst[n][k] = *(const LAS bf16x8*)(lds + PG8_SB(b, h) + boff + n * 2048 + k * 1024); } while (0)
; #define PG8_MMA(ai, bj, At, Bt) do { __builtin_amdgcn_s_setprio(1); _Pragma("unroll") for (int m = 0; m < 4; ++m) _Pragma("unroll") for (int n = 0; n < 2; ++n) _Pragma("unroll") for (int k = 0; k < 2; ++k) \
;         acc[ai][bj][m][n] = __builtin_amdgcn_mfma_f32_16x16x32_bf16(Bt[n][k], At[m][k], acc[ai][bj][m][n], 0, 0, 0); __builtin_amdgcn_s_setprio(0); } while (0)
; #define PG8_WAIT_V(n) asm volatile("s_waitcnt vmcnt(" #n ")" ::: "memory")
; #define PG8_WAIT_L(n) asm volatile("s_waitcnt lgkmcnt(" #n ")" ::: "memory")
; #define PG8_BAR __builtin_amdgcn_s_barrier()
; #define PG8_SCHED __builtin_amdgcn_sched_barrier(0)
; template <class Epi, class Sched>
; DI void gemm_phase(const int wv, LAS unsigned char* lds, const int lda, const int ldb, const int K, const Sched& S, const Epi& E) {
;     ...
;             PG8_WAIT_V(8); PG8_WAIT_L(0); PG8_BAR; PG8_MMA(1, 0, At, B0); PG8_MMA(1, 1, At, B1); PG8_BAR; PG8_SCHED;
;             PG8_LDB(B0, 1, 0); PG8_LDB(B1, 1, 1); PG8_SCHED; PG8_LDA(At, 1, 0); PG8_STAGE(PG8_SA(0, 1), a2 + hstepA, voffA);
;             PG8_WAIT_V(8); PG8_WAIT_L(0); PG8_BAR; PG8_MMA(0, 0, At, B0); PG8_MMA(0, 1, At, B1); PG8_BAR; PG8_SCHED;
;             PG8_LDA(At, 1, 1); PG8_STAGE(PG8_SB(1, 0), b3, voffB); PG8_STAGE(PG8_SB(1, 1), b3 + hstepB, voffB); PG8_STAGE(PG8_SA(1, 0), a3, voffA);
;             PG8_WAIT_V(8); PG8_WAIT_L(0); PG8_BAR; PG8_MMA(1, 0, At, B0); PG8_MMA(1, 1, At, B1); PG8_BAR; PG8_SCHED;
	v_mfma_f32_16x16x32_bf16 v[60:63], v[142:145], v[180:183], v[60:63]
	v_mfma_f32_16x16x32_bf16 v[56:59], v[150:153], v[180:183], v[56:59]
	v_mfma_f32_16x16x32_bf16 v[44:47], v[142:145], v[188:191], v[44:47]
	v_mfma_f32_16x16x32_bf16 v[40:43], v[150:153], v[188:191], v[40:43]
	v_mfma_f32_16x16x32_bf16 v[28:31], v[142:145], v[196:199], v[28:31]
	v_mfma_f32_16x16x32_bf16 v[24:27], v[150:153], v[196:199], v[24:27]
	v_mfma_f32_16x16x32_bf16 v[12:15], v[142:145], v[214:217], v[12:15]
	v_mfma_f32_16x16x32_bf16 v[8:11], v[150:153], v[214:217], v[8:11]
	v_mfma_f32_16x16x32_bf16 v[60:63], v[146:149], v[184:187], v[60:63]
	v_mfma_f32_16x16x32_bf16 v[56:59], v[154:157], v[184:187], v[56:59]
	v_mfma_f32_16x16x32_bf16 v[44:47], v[146:149], v[192:195], v[44:47]
	v_mfma_f32_16x16x32_bf16 v[40:43], v[154:157], v[192:195], v[40:43]
	v_mfma_f32_16x16x32_bf16 v[28:31], v[146:149], v[210:213], v[28:31]
	v_mfma_f32_16x16x32_bf16 v[24:27], v[154:157], v[210:213], v[24:27]
	v_mfma_f32_16x16x32_bf16 v[12:15], v[146:149], v[218:221], v[12:15]
	v_mfma_f32_16x16x32_bf16 v[8:11], v[154:157], v[218:221], v[8:11]
	v_mfma_f32_16x16x32_bf16 v[52:55], v[162:165], v[180:183], v[52:55]
	v_mfma_f32_16x16x32_bf16 v[48:51], v[172:175], v[180:183], v[48:51]
	v_mfma_f32_16x16x32_bf16 v[36:39], v[162:165], v[188:191], v[36:39]
	v_mfma_f32_16x16x32_bf16 v[32:35], v[172:175], v[188:191], v[32:35]
	v_mfma_f32_16x16x32_bf16 v[20:23], v[162:165], v[196:199], v[20:23]
	v_mfma_f32_16x16x32_bf16 v[16:19], v[172:175], v[196:199], v[16:19]
	v_mfma_f32_16x16x32_bf16 v[4:7], v[162:165], v[214:217], v[4:7]
	v_mfma_f32_16x16x32_bf16 v[0:3], v[172:175], v[214:217], v[0:3]
	v_mfma_f32_16x16x32_bf16 v[52:55], v[168:171], v[184:187], v[52:55]
	v_mfma_f32_16x16x32_bf16 v[48:51], v[176:179], v[184:187], v[48:51]
	v_mfma_f32_16x16x32_bf16 v[36:39], v[168:171], v[192:195], v[36:39]
	v_mfma_f32_16x16x32_bf16 v[32:35], v[176:179], v[192:195], v[32:35]
	v_mfma_f32_16x16x32_bf16 v[20:23], v[168:171], v[210:213], v[20:23]
	v_mfma_f32_16x16x32_bf16 v[16:19], v[176:179], v[210:213], v[16:19]
	v_mfma_f32_16x16x32_bf16 v[4:7], v[168:171], v[218:221], v[4:7]
	v_mfma_f32_16x16x32_bf16 v[0:3], v[176:179], v[218:221], v[0:3]
	s_barrier
	s_add_i32 s42, 0, 0x18000
	s_add_i32 s43, 0, 0x1c000
	v_add_u32_e32 v154, s42, v139
	v_add_u32_e32 v176, s43, v139
	ds_read_b128 v[142:145], v154
	ds_read_b128 v[146:149], v154 offset:1024
	ds_read_b128 v[150:153], v154 offset:2048
	ds_read_b128 v[154:157], v154 offset:3072
	ds_read_b128 v[162:165], v176
	ds_read_b128 v[168:171], v176 offset:1024
	ds_read_b128 v[172:175], v176 offset:2048
	ds_read_b128 v[176:179], v176 offset:3072
	s_add_u32 s22, s22, 0x80000
	s_addc_u32 s23, s23, 0
	s_mov_b32 m0, s31
	v_lshl_add_u64 v[228:229], s[22:23], 0, v[132:133]
	ds_read_b128 v[180:183], v141 offset:32768
	ds_read_b128 v[184:187], v141 offset:33792
	ds_read_b128 v[188:191], v141 offset:34816
	ds_read_b128 v[192:195], v141 offset:35840
	ds_read_b128 v[196:199], v141 offset:36864
	ds_read_b128 v[210:213], v141 offset:37888
	ds_read_b128 v[214:217], v141 offset:38912
	ds_read_b128 v[218:221], v141 offset:39936
	global_load_lds_dwordx4 v[228:229], off
	v_lshl_add_u64 v[228:229], s[22:23], 0, v[130:131]
	s_mov_b32 m0, s34
	s_nop 0
	global_load_lds_dwordx4 v[228:229], off
	s_waitcnt vmcnt(8) lgkmcnt(0)
	s_barrier
	v_mfma_f32_16x16x32_bf16 v[124:127], v[142:145], v[180:183], v[124:127]
	v_mfma_f32_16x16x32_bf16 v[120:123], v[150:153], v[180:183], v[120:123]
	v_mfma_f32_16x16x32_bf16 v[108:111], v[142:145], v[188:191], v[108:111]
	v_mfma_f32_16x16x32_bf16 v[104:107], v[150:153], v[188:191], v[104:107]
	v_mfma_f32_16x16x32_bf16 v[92:95], v[142:145], v[196:199], v[92:95]
	v_mfma_f32_16x16x32_bf16 v[88:91], v[150:153], v[196:199], v[88:91]
	v_mfma_f32_16x16x32_bf16 v[76:79], v[142:145], v[214:217], v[76:79]
	v_mfma_f32_16x16x32_bf16 v[72:75], v[150:153], v[214:217], v[72:75]
	v_mfma_f32_16x16x32_bf16 v[124:127], v[146:149], v[184:187], v[124:127]
	v_mfma_f32_16x16x32_bf16 v[120:123], v[154:157], v[184:187], v[120:123]
	v_mfma_f32_16x16x32_bf16 v[108:111], v[146:149], v[192:195], v[108:111]
	v_mfma_f32_16x16x32_bf16 v[104:107], v[154:157], v[192:195], v[104:107]
	v_mfma_f32_16x16x32_bf16 v[92:95], v[146:149], v[210:213], v[92:95]
	v_mfma_f32_16x16x32_bf16 v[88:91], v[154:157], v[210:213], v[88:91]
	v_mfma_f32_16x16x32_bf16 v[76:79], v[146:149], v[218:221], v[76:79]
	v_mfma_f32_16x16x32_bf16 v[72:75], v[154:157], v[218:221], v[72:75]
	v_mfma_f32_16x16x32_bf16 v[116:119], v[162:165], v[180:183], v[116:119]
	v_mfma_f32_16x16x32_bf16 v[112:115], v[172:175], v[180:183], v[112:115]
	v_mfma_f32_16x16x32_bf16 v[100:103], v[162:165], v[188:191], v[100:103]
	v_mfma_f32_16x16x32_bf16 v[96:99], v[172:175], v[188:191], v[96:99]
	v_mfma_f32_16x16x32_bf16 v[84:87], v[162:165], v[196:199], v[84:87]
	v_mfma_f32_16x16x32_bf16 v[80:83], v[172:175], v[196:199], v[80:83]
	v_mfma_f32_16x16x32_bf16 v[68:71], v[162:165], v[214:217], v[68:71]
	v_mfma_f32_16x16x32_bf16 v[64:67], v[172:175], v[214:217], v[64:67]
	v_mfma_f32_16x16x32_bf16 v[116:119], v[168:171], v[184:187], v[116:119]
	v_mfma_f32_16x16x32_bf16 v[112:115], v[176:179], v[184:187], v[112:115]
	v_mfma_f32_16x16x32_bf16 v[100:103], v[168:171], v[192:195], v[100:103]
	v_mfma_f32_16x16x32_bf16 v[96:99], v[176:179], v[192:195], v[96:99]
	v_mfma_f32_16x16x32_bf16 v[84:87], v[168:171], v[210:213], v[84:87]
	v_mfma_f32_16x16x32_bf16 v[80:83], v[176:179], v[210:213], v[80:83]
	v_mfma_f32_16x16x32_bf16 v[68:71], v[168:171], v[218:221], v[68:71]
	v_mfma_f32_16x16x32_bf16 v[64:67], v[176:179], v[218:221], v[64:67]
	s_barrier
; #define PG8_STAGE(bufoff, gbase, voff) do { _Pragma("unroll") for (int _i = 0; _i < 2; ++_i) \
;         __builtin_amdgcn_global_load_lds((const unsigned*)((const char*)(gbase) + (voff)[_i]), (LAS unsigned*)(lds + (bufoff) + ldsw + _i * 8192), 16, 0, 0); } while (0)
; #define PG8_LDA(dst, b, h) do { _Pragma("unroll") for (int m = 0; m < 4; ++m) _Pragma("unroll") for (int k = 0; k < 2; ++k) dst[m][k] = *(const LAS bf16x8*)(lds + PG8_SA(b, h) + aoff + m * 2048 + k * 1024); } while (0)
; #define PG8_LDB(dst, b, h) do { _Pragma("unroll") for (int n = 0; n < 2; ++n) _Pragma("unroll") for (int k = 0; k < 2; ++k) dst[n][k] = *(const LAS bf16x8*)(lds + PG8_SB(b, h) + boff + n * 2048 + k * 1024); } while (0)
; #define PG8_MMA(ai, bj, At, Bt) do { __builtin_amdgcn_s_setprio(1); _Pragma("unroll") for (int m = 0; m < 4; ++m) _Pragma("unroll") for (int n = 0; n < 2; ++n) _Pragma("unroll") for (int k = 0; k < 2; ++k) \
;         acc[ai][bj][m][n] = __builtin_amdgcn_mfma_f32_16x16x32_bf16(Bt[n][k], At[m][k], acc[ai][bj][m][n], 0, 0, 0); __builtin_amdgcn_s_setprio(0); } while (0)
; #define PG8_WAIT_V(n) asm volatile("s_waitcnt vmcnt(" #n ")" ::: "memory")
; #define PG8_WAIT_L(n) asm volatile("s_waitcnt lgkmcnt(" #n ")" ::: "memory")
; #define PG8_BAR __builtin_amdgcn_s_barrier()
; #define PG8_SCHED __builtin_amdgcn_sched_barrier(0)
; template <class Epi, class Sched>
; DI void gemm_phase(const int wv, LAS unsigned char* lds, const int lda, const int ldb, const int K, const Sched& S, const Epi& E) {
;     ...
;             PG8_LDB(B0, 1, 0); PG8_LDB(B1, 1, 1); PG8_SCHED; PG8_LDA(At, 1, 0); PG8_STAGE(PG8_SA(0, 1), a2 + hstepA, voffA);
;             PG8_WAIT_V(8); PG8_WAIT_L(0); PG8_BAR; PG8_MMA(0, 0, At, B0); PG8_MMA(0, 1, At, B1); PG8_BAR; PG8_SCHED;
;             PG8_LDA(At, 1, 1); PG8_STAGE(PG8_SB(1, 0), b3, voffB); PG8_STAGE(PG8_SB(1, 1), b3 + hstepB, voffB); PG8_STAGE(PG8_SA(1, 0), a3, voffA);
;             PG8_WAIT_V(8); PG8_WAIT_L(0); PG8_BAR; PG8_MMA(1, 0, At, B0); PG8_MMA(1, 1, At, B1); PG8_BAR; PG8_SCHED;
;         }
;         if (wr == 0) PG8_BAR;
	s_add_i32 s22, s42, s28
	v_lshl_add_u64 v[158:159], v[158:159], 0, s[78:79]
	s_mov_b32 m0, s22
	ds_read_b128 v[180:183], v141 offset:49152
	ds_read_b128 v[184:187], v141 offset:50176
	ds_read_b128 v[188:191], v141 offset:51200
	ds_read_b128 v[192:195], v141 offset:52224
	ds_read_b128 v[196:199], v141 offset:53248
	ds_read_b128 v[210:213], v141 offset:54272
	ds_read_b128 v[214:217], v141 offset:55296
	ds_read_b128 v[218:221], v141 offset:56320
	global_load_lds_dwordx4 v[158:159], off
	s_add_i32 m0, s22, 0x2000
	s_add_u32 s20, s20, 0x80080
	v_lshl_add_u64 v[158:159], v[222:223], 0, s[78:79]
	s_addc_u32 s21, s21, 0
	s_add_i32 s22, s43, s28
	global_load_lds_dwordx4 v[158:159], off
	v_lshl_add_u64 v[158:159], s[20:21], 0, v[160:161]
	s_mov_b32 m0, s22
	s_nop 0
	global_load_lds_dwordx4 v[158:159], off
	v_lshl_add_u64 v[158:159], s[20:21], 0, v[128:129]
	s_add_i32 m0, s22, 0x2000
	s_nop 0
	global_load_lds_dwordx4 v[158:159], off
	v_lshl_add_u64 v[158:159], v[224:225], 0, s[78:79]
	s_mov_b32 m0, s35
	s_nop 0
	global_load_lds_dwordx4 v[158:159], off
	v_lshl_add_u64 v[158:159], v[226:227], 0, s[78:79]
	s_mov_b32 m0, s36
	s_nop 0
	global_load_lds_dwordx4 v[158:159], off
	s_waitcnt vmcnt(8) lgkmcnt(0)
	s_barrier
	v_mfma_f32_16x16x32_bf16 v[60:63], v[142:145], v[180:183], v[60:63]
	v_mfma_f32_16x16x32_bf16 v[56:59], v[150:153], v[180:183], v[56:59]
	v_mfma_f32_16x16x32_bf16 v[44:47], v[142:145], v[188:191], v[44:47]
	v_mfma_f32_16x16x32_bf16 v[40:43], v[150:153], v[188:191], v[40:43]
	v_mfma_f32_16x16x32_bf16 v[28:31], v[142:145], v[196:199], v[28:31]
	v_mfma_f32_16x16x32_bf16 v[24:27], v[150:153], v[196:199], v[24:27]
	v_mfma_f32_16x16x32_bf16 v[12:15], v[142:145], v[214:217], v[12:15]
	v_mfma_f32_16x16x32_bf16 v[8:11], v[150:153], v[214:217], v[8:11]
	v_mfma_f32_16x16x32_bf16 v[60:63], v[146:149], v[184:187], v[60:63]
	v_mfma_f32_16x16x32_bf16 v[56:59], v[154:157], v[184:187], v[56:59]
	v_mfma_f32_16x16x32_bf16 v[44:47], v[146:149], v[192:195], v[44:47]
	v_mfma_f32_16x16x32_bf16 v[40:43], v[154:157], v[192:195], v[40:43]
	v_mfma_f32_16x16x32_bf16 v[28:31], v[146:149], v[210:213], v[28:31]
	v_mfma_f32_16x16x32_bf16 v[24:27], v[154:157], v[210:213], v[24:27]
	v_mfma_f32_16x16x32_bf16 v[12:15], v[146:149], v[218:221], v[12:15]
	v_mfma_f32_16x16x32_bf16 v[8:11], v[154:157], v[218:221], v[8:11]
	v_mfma_f32_16x16x32_bf16 v[52:55], v[162:165], v[180:183], v[52:55]
	v_mfma_f32_16x16x32_bf16 v[48:51], v[172:175], v[180:183], v[48:51]
	v_mfma_f32_16x16x32_bf16 v[36:39], v[162:165], v[188:191], v[36:39]
	v_mfma_f32_16x16x32_bf16 v[32:35], v[172:175], v[188:191], v[32:35]
	v_mfma_f32_16x16x32_bf16 v[20:23], v[162:165], v[196:199], v[20:23]
	v_mfma_f32_16x16x32_bf16 v[16:19], v[172:175], v[196:199], v[16:19]
	v_mfma_f32_16x16x32_bf16 v[4:7], v[162:165], v[214:217], v[4:7]
	v_mfma_f32_16x16x32_bf16 v[0:3], v[172:175], v[214:217], v[0:3]
	v_mfma_f32_16x16x32_bf16 v[52:55], v[168:171], v[184:187], v[52:55]
	v_mfma_f32_16x16x32_bf16 v[48:51], v[176:179], v[184:187], v[48:51]
	v_mfma_f32_16x16x32_bf16 v[36:39], v[168:171], v[192:195], v[36:39]
	v_mfma_f32_16x16x32_bf16 v[32:35], v[176:179], v[192:195], v[32:35]
	v_mfma_f32_16x16x32_bf16 v[20:23], v[168:171], v[210:213], v[20:23]
	v_mfma_f32_16x16x32_bf16 v[16:19], v[176:179], v[210:213], v[16:19]
	v_mfma_f32_16x16x32_bf16 v[4:7], v[168:171], v[218:221], v[4:7]
	v_mfma_f32_16x16x32_bf16 v[0:3], v[176:179], v[218:221], v[0:3]
	s_barrier
	s_add_i32 s41, s41, 2
	s_add_u32 s13, s13, 0x100
	s_addc_u32 s40, s40, 0
	s_add_u32 s18, s18, 0x100
	s_addc_u32 s19, s19, 0
	s_cmp_gt_u32 s41, 29
	s_cbranch_scc0 .LBB0_825
	s_and_b64 vcc, exec, s[10:11]
	s_cbranch_vccz .LBB0_828
	s_barrier

; #define PG8_STAGE(bufoff, gbase, voff) do { _Pragma("unroll") for (int _i = 0; _i < 2; ++_i) \
;         __builtin_amdgcn_global_load_lds((const unsigned*)((const char*)(gbase) + (voff)[_i]), (LAS unsigned*)(lds + (bufoff) + ldsw + _i * 8192), 16, 0, 0); } while (0)
; #define PG8_LDA(dst, b, h) do { _Pragma("unroll") for (int m = 0; m < 4; ++m) _Pragma("unroll") for (int k = 0; k < 2; ++k) dst[m][k] = *(const LAS bf16x8*)(lds + PG8_SA(b, h) + aoff + m * 2048 + k * 1024); } while (0)
; #define PG8_LDB(dst, b, h) do { _Pragma("unroll") for (int n = 0; n < 2; ++n) _Pragma("unroll") for (int k = 0; k < 2; ++k) dst[n][k] = *(const LAS bf16x8*)(lds + PG8_SB(b, h) + boff + n * 2048 + k * 1024); } while (0)
; #define PG8_MMA(ai, bj, At, Bt) do { __builtin_amdgcn_s_setprio(1); _Pragma("unroll") for (int m = 0; m < 4; ++m) _Pragma("unroll") for (int n = 0; n < 2; ++n) _Pragma("unroll") for (int k = 0; k < 2; ++k) \
;         acc[ai][bj][m][n] = __builtin_amdgcn_mfma_f32_16x16x32_bf16(Bt[n][k], At[m][k], acc[ai][bj][m][n], 0, 0, 0); __builtin_amdgcn_s_setprio(0); } while (0)
; #define PG8_WAIT_V(n) asm volatile("s_waitcnt vmcnt(" #n ")" ::: "memory")
; #define PG8_WAIT_L(n) asm volatile("s_waitcnt lgkmcnt(" #n ")" ::: "memory")
; #define PG8_BAR __builtin_amdgcn_s_barrier()
; #define PG8_SCHED __builtin_amdgcn_sched_barrier(0)
; template <class Epi, class Sched>
; DI void gemm_phase(const int wv, LAS unsigned char* lds, const int lda, const int ldb, const int K, const Sched& S, const Epi& E) {
;     ...
;             const bool last = (t == nt - 2);
;             const char* a1 = cA + (size_t)(t + 1) * kstep;
;             const char* a2 = last ? nA : cA + (size_t)(t + 2) * kstep; const char* b2 = last ? nB : cB + (size_t)(t + 2) * kstep;
;             const char* a3 = a2 + kstep; const char* b3 = b2 + kstep;
;             PG8_LDB(B0, 0, 0); PG8_LDB(B1, 0, 1); PG8_SCHED; PG8_LDA(At, 0, 0); PG8_STAGE(PG8_SA(1, 1), a1 + hstepA, voffA);
;             PG8_WAIT_V(8); PG8_WAIT_L(0); PG8_BAR; PG8_MMA(0, 0, At, B0); PG8_MMA(0, 1, At, B1); PG8_BAR; PG8_SCHED;
;             PG8_LDA(At, 0, 1); PG8_STAGE(PG8_SB(0, 0), b2, voffB); PG8_STAGE(PG8_SB(0, 1), b2 + hstepB, voffB); PG8_STAGE(PG8_SA(0, 0), a2, voffA);
;             PG8_WAIT_V(8); PG8_WAIT_L(0); PG8_BAR; PG8_MMA(1, 0, At, B0); PG8_MMA(1, 1, At, B1); PG8_BAR; PG8_SCHED;
.LBB0_906:
	s_add_u32 s14, s12, 0xffea0080
	s_addc_u32 s15, s13, -1
	s_add_i32 s40, 0, 0x10000
	s_cmpk_eq_i32 s39, 0x54
	s_cselect_b32 s17, s9, s15
	s_cselect_b32 s16, s8, s14
	s_cselect_b32 s15, s11, s38
	s_cselect_b32 s14, s10, s37
	s_add_i32 s42, 0, 0x14000
	v_add_u32_e32 v76, s40, v157
	v_add_u32_e32 v154, s42, v157
	ds_read_b128 v[48:51], v76
	ds_read_b128 v[52:55], v76 offset:1024
	ds_read_b128 v[72:75], v76 offset:2048
	ds_read_b128 v[76:79], v76 offset:3072
	ds_read_b128 v[162:165], v154
	ds_read_b128 v[168:171], v154 offset:1024
	ds_read_b128 v[172:175], v154 offset:2048
	ds_read_b128 v[176:179], v154 offset:3072
	v_lshl_add_u64 v[154:155], s[12:13], 0, v[152:153]
	s_add_i32 m0, s23, 0xc000
	ds_read_b128 v[180:183], v159
	ds_read_b128 v[184:187], v159 offset:1024
	ds_read_b128 v[188:191], v159 offset:2048
	ds_read_b128 v[192:195], v159 offset:3072
	ds_read_b128 v[196:199], v159 offset:4096
	ds_read_b128 v[210:213], v159 offset:5120
	ds_read_b128 v[214:217], v159 offset:6144
	ds_read_b128 v[218:221], v159 offset:7168
	global_load_lds_dwordx4 v[154:155], off
	v_lshl_add_u64 v[154:155], s[12:13], 0, v[150:151]
	s_add_i32 m0, s23, 0xe000
	s_nop 0
	global_load_lds_dwordx4 v[154:155], off
	s_waitcnt vmcnt(8) lgkmcnt(0)
	s_barrier
	v_mfma_f32_16x16x32_bf16 v[140:143], v[48:51], v[180:183], v[140:143]
	v_mfma_f32_16x16x32_bf16 v[136:139], v[72:75], v[180:183], v[136:139]
	v_mfma_f32_16x16x32_bf16 v[124:127], v[48:51], v[188:191], v[124:127]
	v_mfma_f32_16x16x32_bf16 v[120:123], v[72:75], v[188:191], v[120:123]
	v_mfma_f32_16x16x32_bf16 v[116:119], v[48:51], v[196:199], v[116:119]
	v_mfma_f32_16x16x32_bf16 v[112:115], v[72:75], v[196:199], v[112:115]
	v_mfma_f32_16x16x32_bf16 v[100:103], v[48:51], v[214:217], v[100:103]
	v_mfma_f32_16x16x32_bf16 v[96:99], v[72:75], v[214:217], v[96:99]
	v_mfma_f32_16x16x32_bf16 v[140:143], v[52:55], v[184:187], v[140:143]
	v_mfma_f32_16x16x32_bf16 v[136:139], v[76:79], v[184:187], v[136:139]
	v_mfma_f32_16x16x32_bf16 v[124:127], v[52:55], v[192:195], v[124:127]
	v_mfma_f32_16x16x32_bf16 v[120:123], v[76:79], v[192:195], v[120:123]
	v_mfma_f32_16x16x32_bf16 v[116:119], v[52:55], v[210:213], v[116:119]
	v_mfma_f32_16x16x32_bf16 v[112:115], v[76:79], v[210:213], v[112:115]
	v_mfma_f32_16x16x32_bf16 v[100:103], v[52:55], v[218:221], v[100:103]
	v_mfma_f32_16x16x32_bf16 v[96:99], v[76:79], v[218:221], v[96:99]
	v_mfma_f32_16x16x32_bf16 v[132:135], v[162:165], v[180:183], v[132:135]
	v_mfma_f32_16x16x32_bf16 v[128:131], v[172:175], v[180:183], v[128:131]
	v_mfma_f32_16x16x32_bf16 v[108:111], v[162:165], v[188:191], v[108:111]
	v_mfma_f32_16x16x32_bf16 v[104:107], v[172:175], v[188:191], v[104:107]
	v_mfma_f32_16x16x32_bf16 v[92:95], v[162:165], v[196:199], v[92:95]
	v_mfma_f32_16x16x32_bf16 v[88:91], v[172:175], v[196:199], v[88:91]
	v_mfma_f32_16x16x32_bf16 v[84:87], v[162:165], v[214:217], v[84:87]
	v_mfma_f32_16x16x32_bf16 v[80:83], v[172:175], v[214:217], v[80:83]
	v_mfma_f32_16x16x32_bf16 v[132:135], v[168:171], v[184:187], v[132:135]
	v_mfma_f32_16x16x32_bf16 v[128:131], v[176:179], v[184:187], v[128:131]
	v_mfma_f32_16x16x32_bf16 v[108:111], v[168:171], v[192:195], v[108:111]
	v_mfma_f32_16x16x32_bf16 v[104:107], v[176:179], v[192:195], v[104:107]
	v_mfma_f32_16x16x32_bf16 v[92:95], v[168:171], v[210:213], v[92:95]
	v_mfma_f32_16x16x32_bf16 v[88:91], v[176:179], v[210:213], v[88:91]
	v_mfma_f32_16x16x32_bf16 v[84:87], v[168:171], v[218:221], v[84:87]
	v_mfma_f32_16x16x32_bf16 v[80:83], v[176:179], v[218:221], v[80:83]
	s_barrier
	s_add_i32 s40, s40, s22
	v_lshl_add_u64 v[154:155], s[14:15], 0, v[160:161]
	s_mov_b32 m0, s40
	ds_read_b128 v[180:183], v159 offset:16384
	ds_read_b128 v[184:187], v159 offset:17408
	ds_read_b128 v[188:191], v159 offset:18432
	ds_read_b128 v[192:195], v159 offset:19456
	ds_read_b128 v[196:199], v159 offset:20480
	ds_read_b128 v[210:213], v159 offset:21504
	ds_read_b128 v[214:217], v159 offset:22528
	ds_read_b128 v[218:221], v159 offset:23552
	global_load_lds_dwordx4 v[154:155], off
	s_add_i32 m0, s40, 0x2000
	s_add_u32 s40, s14, 0x160000
	v_lshl_add_u64 v[222:223], s[14:15], 0, v[144:145]
	s_addc_u32 s41, s15, 0
	s_add_i32 s42, s42, s22
	global_load_lds_dwordx4 v[222:223], off
	v_lshl_add_u64 v[224:225], s[40:41], 0, v[160:161]
	s_mov_b32 m0, s42
	v_lshl_add_u64 v[226:227], s[16:17], 0, v[146:147]
	global_load_lds_dwordx4 v[224:225], off
	v_lshl_add_u64 v[224:225], s[40:41], 0, v[144:145]
	s_add_i32 m0, s42, 0x2000
	s_nop 0
	global_load_lds_dwordx4 v[224:225], off
	v_lshl_add_u64 v[224:225], s[16:17], 0, v[148:149]
	s_mov_b32 m0, s23
	s_nop 0
	global_load_lds_dwordx4 v[224:225], off
	s_mov_b32 m0, s24
	s_nop 0
	global_load_lds_dwordx4 v[226:227], off
	s_waitcnt vmcnt(8) lgkmcnt(0)
	s_barrier
; #define PG8_STAGE(bufoff, gbase, voff) do { _Pragma("unroll") for (int _i = 0; _i < 2; ++_i) \
;         __builtin_amdgcn_global_load_lds((const unsigned*)((const char*)(gbase) + (voff)[_i]), (LAS unsigned*)(lds + (bufoff) + ldsw + _i * 8192), 16, 0, 0); } while (0)
; #define PG8_LDA(dst, b, h) do { _Pragma("unroll") for (int m = 0; m < 4; ++m) _Pragma("unroll") for (int k = 0; k < 2; ++k) dst[m][k] = *(const LAS bf16x8*)(lds + PG8_SA(b, h) + aoff + m * 2048 + k * 1024); } while (0)
; #define PG8_LDB(dst, b, h) do { _Pragma("unroll") for (int n = 0; n < 2; ++n) _Pragma("unroll") for (int k = 0; k < 2; ++k) dst[n][k] = *(const LAS bf16x8*)(lds + PG8_SB(b, h) + boff + n * 2048 + k * 1024); } while (0)
; #define PG8_MMA(ai, bj, At, Bt) do { __builtin_amdgcn_s_setprio(1); _Pragma("unroll") for (int m = 0; m < 4; ++m) _Pragma("unroll") for (int n = 0; n < 2; ++n) _Pragma("unroll") for (int k = 0; k < 2; ++k) \
;         acc[ai][bj][m][n] = __builtin_amdgcn_mfma_f32_16x16x32_bf16(Bt[n][k], At[m][k], acc[ai][bj][m][n], 0, 0, 0); __builtin_amdgcn_s_setprio(0); } while (0)
; #define PG8_WAIT_V(n) asm volatile("s_waitcnt vmcnt(" #n ")" ::: "memory")
; #define PG8_WAIT_L(n) asm volatile("s_waitcnt lgkmcnt(" #n ")" ::: "memory")
; #define PG8_BAR __builtin_amdgcn_s_barrier()
; #define PG8_SCHED __builtin_amdgcn_sched_barrier(0)
; template <class Epi, class Sched>
; DI void gemm_phase(const int wv, LAS unsigned char* lds, const int lda, const int ldb, const int K, const Sched& S, const Epi& E) {
;     ...
;             PG8_WAIT_V(8); PG8_WAIT_L(0); PG8_BAR; PG8_MMA(1, 0, At, B0); PG8_MMA(1, 1, At, B1); PG8_BAR; PG8_SCHED;
;             PG8_LDB(B0, 1, 0); PG8_LDB(B1, 1, 1); PG8_SCHED; PG8_LDA(At, 1, 0); PG8_STAGE(PG8_SA(0, 1), a2 + hstepA, voffA);
;             PG8_WAIT_V(8); PG8_WAIT_L(0); PG8_BAR; PG8_MMA(0, 0, At, B0); PG8_MMA(0, 1, At, B1); PG8_BAR; PG8_SCHED;
;             PG8_LDA(At, 1, 1); PG8_STAGE(PG8_SB(1, 0), b3, voffB); PG8_STAGE(PG8_SB(1, 1), b3 + hstepB, voffB); PG8_STAGE(PG8_SA(1, 0), a3, voffA);
;             PG8_WAIT_V(8); PG8_WAIT_L(0); PG8_BAR; PG8_MMA(1, 0, At, B0); PG8_MMA(1, 1, At, B1); PG8_BAR; PG8_SCHED;
	v_mfma_f32_16x16x32_bf16 v[68:71], v[48:51], v[180:183], v[68:71]
	v_mfma_f32_16x16x32_bf16 v[64:67], v[72:75], v[180:183], v[64:67]
	v_mfma_f32_16x16x32_bf16 v[44:47], v[48:51], v[188:191], v[44:47]
	v_mfma_f32_16x16x32_bf16 v[40:43], v[72:75], v[188:191], v[40:43]
	v_mfma_f32_16x16x32_bf16 v[28:31], v[48:51], v[196:199], v[28:31]
	v_mfma_f32_16x16x32_bf16 v[24:27], v[72:75], v[196:199], v[24:27]
	v_mfma_f32_16x16x32_bf16 v[12:15], v[48:51], v[214:217], v[12:15]
	v_mfma_f32_16x16x32_bf16 v[8:11], v[72:75], v[214:217], v[8:11]
	v_mfma_f32_16x16x32_bf16 v[68:71], v[52:55], v[184:187], v[68:71]
	v_mfma_f32_16x16x32_bf16 v[64:67], v[76:79], v[184:187], v[64:67]
	v_mfma_f32_16x16x32_bf16 v[44:47], v[52:55], v[192:195], v[44:47]
	v_mfma_f32_16x16x32_bf16 v[40:43], v[76:79], v[192:195], v[40:43]
	v_mfma_f32_16x16x32_bf16 v[28:31], v[52:55], v[210:213], v[28:31]
	v_mfma_f32_16x16x32_bf16 v[24:27], v[76:79], v[210:213], v[24:27]
	v_mfma_f32_16x16x32_bf16 v[12:15], v[52:55], v[218:221], v[12:15]
	v_mfma_f32_16x16x32_bf16 v[8:11], v[76:79], v[218:221], v[8:11]
	v_mfma_f32_16x16x32_bf16 v[36:39], v[162:165], v[188:191], v[36:39]
	v_mfma_f32_16x16x32_bf16 v[32:35], v[172:175], v[188:191], v[32:35]
	v_mfma_f32_16x16x32_bf16 v[20:23], v[162:165], v[196:199], v[20:23]
	v_mfma_f32_16x16x32_bf16 v[16:19], v[172:175], v[196:199], v[16:19]
	v_mfma_f32_16x16x32_bf16 v[4:7], v[162:165], v[214:217], v[4:7]
	v_mfma_f32_16x16x32_bf16 v[0:3], v[172:175], v[214:217], v[0:3]
	v_mfma_f32_16x16x32_bf16 v[48:51], v[162:165], v[180:183], v[60:63]
	v_mfma_f32_16x16x32_bf16 v[52:55], v[172:175], v[180:183], v[56:59]
	v_mfma_f32_16x16x32_bf16 v[36:39], v[168:171], v[192:195], v[36:39]
	v_mfma_f32_16x16x32_bf16 v[32:35], v[176:179], v[192:195], v[32:35]
	v_mfma_f32_16x16x32_bf16 v[20:23], v[168:171], v[210:213], v[20:23]
	v_mfma_f32_16x16x32_bf16 v[16:19], v[176:179], v[210:213], v[16:19]
	v_mfma_f32_16x16x32_bf16 v[4:7], v[168:171], v[218:221], v[4:7]
	v_mfma_f32_16x16x32_bf16 v[0:3], v[176:179], v[218:221], v[0:3]
	v_mfma_f32_16x16x32_bf16 v[48:51], v[168:171], v[184:187], v[48:51]
	v_mfma_f32_16x16x32_bf16 v[52:55], v[176:179], v[184:187], v[52:55]
	s_barrier
	s_add_i32 s40, 0, 0x18000
	s_add_i32 s41, 0, 0x1c000
	v_add_u32_e32 v76, s40, v157
	v_add_u32_e32 v176, s41, v157
	ds_read_b128 v[56:59], v76
	ds_read_b128 v[60:63], v76 offset:1024
	ds_read_b128 v[72:75], v76 offset:2048
	ds_read_b128 v[76:79], v76 offset:3072
	ds_read_b128 v[162:165], v176
	ds_read_b128 v[168:171], v176 offset:1024
	ds_read_b128 v[172:175], v176 offset:2048
	ds_read_b128 v[176:179], v176 offset:3072
	s_add_u32 s16, s16, 0x160000
	s_addc_u32 s17, s17, 0
	s_mov_b32 m0, s25
	v_lshl_add_u64 v[228:229], s[16:17], 0, v[148:149]
	ds_read_b128 v[180:183], v159 offset:32768
	ds_read_b128 v[184:187], v159 offset:33792
	ds_read_b128 v[188:191], v159 offset:34816
	ds_read_b128 v[192:195], v159 offset:35840
	ds_read_b128 v[196:199], v159 offset:36864
	ds_read_b128 v[210:213], v159 offset:37888
	ds_read_b128 v[214:217], v159 offset:38912
	ds_read_b128 v[218:221], v159 offset:39936
	global_load_lds_dwordx4 v[228:229], off
	v_lshl_add_u64 v[228:229], s[16:17], 0, v[146:147]
	s_mov_b32 m0, s26
	s_nop 0
	global_load_lds_dwordx4 v[228:229], off
	s_waitcnt vmcnt(8) lgkmcnt(0)
	s_barrier
	v_mfma_f32_16x16x32_bf16 v[140:143], v[56:59], v[180:183], v[140:143]
	v_mfma_f32_16x16x32_bf16 v[136:139], v[72:75], v[180:183], v[136:139]
	v_mfma_f32_16x16x32_bf16 v[124:127], v[56:59], v[188:191], v[124:127]
	v_mfma_f32_16x16x32_bf16 v[120:123], v[72:75], v[188:191], v[120:123]
	v_mfma_f32_16x16x32_bf16 v[116:119], v[56:59], v[196:199], v[116:119]
	v_mfma_f32_16x16x32_bf16 v[112:115], v[72:75], v[196:199], v[112:115]
	v_mfma_f32_16x16x32_bf16 v[100:103], v[56:59], v[214:217], v[100:103]
	v_mfma_f32_16x16x32_bf16 v[96:99], v[72:75], v[214:217], v[96:99]
	v_mfma_f32_16x16x32_bf16 v[140:143], v[60:63], v[184:187], v[140:143]
	v_mfma_f32_16x16x32_bf16 v[136:139], v[76:79], v[184:187], v[136:139]
	v_mfma_f32_16x16x32_bf16 v[124:127], v[60:63], v[192:195], v[124:127]
	v_mfma_f32_16x16x32_bf16 v[120:123], v[76:79], v[192:195], v[120:123]
	v_mfma_f32_16x16x32_bf16 v[116:119], v[60:63], v[210:213], v[116:119]
	v_mfma_f32_16x16x32_bf16 v[112:115], v[76:79], v[210:213], v[112:115]
	v_mfma_f32_16x16x32_bf16 v[100:103], v[60:63], v[218:221], v[100:103]
	v_mfma_f32_16x16x32_bf16 v[96:99], v[76:79], v[218:221], v[96:99]
	v_mfma_f32_16x16x32_bf16 v[132:135], v[162:165], v[180:183], v[132:135]
	v_mfma_f32_16x16x32_bf16 v[128:131], v[172:175], v[180:183], v[128:131]
	v_mfma_f32_16x16x32_bf16 v[108:111], v[162:165], v[188:191], v[108:111]
	v_mfma_f32_16x16x32_bf16 v[104:107], v[172:175], v[188:191], v[104:107]
	v_mfma_f32_16x16x32_bf16 v[92:95], v[162:165], v[196:199], v[92:95]
	v_mfma_f32_16x16x32_bf16 v[88:91], v[172:175], v[196:199], v[88:91]
	v_mfma_f32_16x16x32_bf16 v[84:87], v[162:165], v[214:217], v[84:87]
	v_mfma_f32_16x16x32_bf16 v[80:83], v[172:175], v[214:217], v[80:83]
	v_mfma_f32_16x16x32_bf16 v[132:135], v[168:171], v[184:187], v[132:135]
	v_mfma_f32_16x16x32_bf16 v[128:131], v[176:179], v[184:187], v[128:131]
	v_mfma_f32_16x16x32_bf16 v[108:111], v[168:171], v[192:195], v[108:111]
	v_mfma_f32_16x16x32_bf16 v[104:107], v[176:179], v[192:195], v[104:107]
	v_mfma_f32_16x16x32_bf16 v[92:95], v[168:171], v[210:213], v[92:95]
	v_mfma_f32_16x16x32_bf16 v[88:91], v[176:179], v[210:213], v[88:91]
	v_mfma_f32_16x16x32_bf16 v[84:87], v[168:171], v[218:221], v[84:87]
	v_mfma_f32_16x16x32_bf16 v[80:83], v[176:179], v[218:221], v[80:83]
	s_barrier
; #define PG8_STAGE(bufoff, gbase, voff) do { _Pragma("unroll") for (int _i = 0; _i < 2; ++_i) \
;         __builtin_amdgcn_global_load_lds((const unsigned*)((const char*)(gbase) + (voff)[_i]), (LAS unsigned*)(lds + (bufoff) + ldsw + _i * 8192), 16, 0, 0); } while (0)
; #define PG8_LDA(dst, b, h) do { _Pragma("unroll") for (int m = 0; m < 4; ++m) _Pragma("unroll") for (int k = 0; k < 2; ++k) dst[m][k] = *(const LAS bf16x8*)(lds + PG8_SA(b, h) + aoff + m * 2048 + k * 1024); } while (0)
; #define PG8_LDB(dst, b, h) do { _Pragma("unroll") for (int n = 0; n < 2; ++n) _Pragma("unroll") for (int k = 0; k < 2; ++k) dst[n][k] = *(const LAS bf16x8*)(lds + PG8_SB(b, h) + boff + n * 2048 + k * 1024); } while (0)
; #define PG8_MMA(ai, bj, At, Bt) do { __builtin_amdgcn_s_setprio(1); _Pragma("unroll") for (int m = 0; m < 4; ++m) _Pragma("unroll") for (int n = 0; n < 2; ++n) _Pragma("unroll") for (int k = 0; k < 2; ++k) \
;         acc[ai][bj][m][n] = __builtin_amdgcn_mfma_f32_16x16x32_bf16(Bt[n][k], At[m][k], acc[ai][bj][m][n], 0, 0, 0); __builtin_amdgcn_s_setprio(0); } while (0)
; #define PG8_WAIT_V(n) asm volatile("s_waitcnt vmcnt(" #n ")" ::: "memory")
; #define PG8_WAIT_L(n) asm volatile("s_waitcnt lgkmcnt(" #n ")" ::: "memory")
; #define PG8_BAR __builtin_amdgcn_s_barrier()
; #define PG8_SCHED __builtin_amdgcn_sched_barrier(0)
; template <class Epi, class Sched>
; DI void gemm_phase(const int wv, LAS unsigned char* lds, const int lda, const int ldb, const int K, const Sched& S, const Epi& E) {
;     ...
;             PG8_LDB(B0, 1, 0); PG8_LDB(B1, 1, 1); PG8_SCHED; PG8_LDA(At, 1, 0); PG8_STAGE(PG8_SA(0, 1), a2 + hstepA, voffA);
;             PG8_WAIT_V(8); PG8_WAIT_L(0); PG8_BAR; PG8_MMA(0, 0, At, B0); PG8_MMA(0, 1, At, B1); PG8_BAR; PG8_SCHED;
;             PG8_LDA(At, 1, 1); PG8_STAGE(PG8_SB(1, 0), b3, voffB); PG8_STAGE(PG8_SB(1, 1), b3 + hstepB, voffB); PG8_STAGE(PG8_SA(1, 0), a3, voffA);
;             PG8_WAIT_V(8); PG8_WAIT_L(0); PG8_BAR; PG8_MMA(1, 0, At, B0); PG8_MMA(1, 1, At, B1); PG8_BAR; PG8_SCHED;
;         }
;         if (wr == 0) PG8_BAR;
	s_add_i32 s16, s40, s22
	v_lshl_add_u64 v[154:155], v[154:155], 0, s[78:79]
	s_mov_b32 m0, s16
	ds_read_b128 v[180:183], v159 offset:49152
	ds_read_b128 v[184:187], v159 offset:50176
	ds_read_b128 v[188:191], v159 offset:51200
	ds_read_b128 v[192:195], v159 offset:52224
	ds_read_b128 v[196:199], v159 offset:53248
	ds_read_b128 v[210:213], v159 offset:54272
	ds_read_b128 v[214:217], v159 offset:55296
	ds_read_b128 v[218:221], v159 offset:56320
	global_load_lds_dwordx4 v[154:155], off
	s_add_i32 m0, s16, 0x2000
	s_add_u32 s14, s14, 0x160080
	v_lshl_add_u64 v[154:155], v[222:223], 0, s[78:79]
	s_addc_u32 s15, s15, 0
	s_add_i32 s16, s41, s22
	global_load_lds_dwordx4 v[154:155], off
	v_lshl_add_u64 v[154:155], s[14:15], 0, v[160:161]
	s_mov_b32 m0, s16
	s_nop 0
	global_load_lds_dwordx4 v[154:155], off
	v_lshl_add_u64 v[154:155], s[14:15], 0, v[144:145]
	s_add_i32 m0, s16, 0x2000
	s_nop 0
	global_load_lds_dwordx4 v[154:155], off
	v_lshl_add_u64 v[154:155], v[224:225], 0, s[78:79]
	s_mov_b32 m0, s29
	s_nop 0
	global_load_lds_dwordx4 v[154:155], off
	v_lshl_add_u64 v[154:155], v[226:227], 0, s[78:79]
	s_mov_b32 m0, s30
	s_nop 0
	global_load_lds_dwordx4 v[154:155], off
	s_waitcnt vmcnt(8) lgkmcnt(0)
	s_barrier
	v_mfma_f32_16x16x32_bf16 v[68:71], v[56:59], v[180:183], v[68:71]
	v_mfma_f32_16x16x32_bf16 v[64:67], v[72:75], v[180:183], v[64:67]
	v_mfma_f32_16x16x32_bf16 v[44:47], v[56:59], v[188:191], v[44:47]
	v_mfma_f32_16x16x32_bf16 v[40:43], v[72:75], v[188:191], v[40:43]
	v_mfma_f32_16x16x32_bf16 v[28:31], v[56:59], v[196:199], v[28:31]
	v_mfma_f32_16x16x32_bf16 v[24:27], v[72:75], v[196:199], v[24:27]
	v_mfma_f32_16x16x32_bf16 v[12:15], v[56:59], v[214:217], v[12:15]
	v_mfma_f32_16x16x32_bf16 v[8:11], v[72:75], v[214:217], v[8:11]
	v_mfma_f32_16x16x32_bf16 v[68:71], v[60:63], v[184:187], v[68:71]
	v_mfma_f32_16x16x32_bf16 v[64:67], v[76:79], v[184:187], v[64:67]
	v_mfma_f32_16x16x32_bf16 v[44:47], v[60:63], v[192:195], v[44:47]
	v_mfma_f32_16x16x32_bf16 v[40:43], v[76:79], v[192:195], v[40:43]
	v_mfma_f32_16x16x32_bf16 v[28:31], v[60:63], v[210:213], v[28:31]
	v_mfma_f32_16x16x32_bf16 v[24:27], v[76:79], v[210:213], v[24:27]
	v_mfma_f32_16x16x32_bf16 v[12:15], v[60:63], v[218:221], v[12:15]
	v_mfma_f32_16x16x32_bf16 v[8:11], v[76:79], v[218:221], v[8:11]
	v_mfma_f32_16x16x32_bf16 v[48:51], v[162:165], v[180:183], v[48:51]
	v_mfma_f32_16x16x32_bf16 v[60:63], v[168:171], v[184:187], v[48:51]
	v_mfma_f32_16x16x32_bf16 v[48:51], v[172:175], v[180:183], v[52:55]
	v_mfma_f32_16x16x32_bf16 v[36:39], v[162:165], v[188:191], v[36:39]
	v_mfma_f32_16x16x32_bf16 v[32:35], v[172:175], v[188:191], v[32:35]
	v_mfma_f32_16x16x32_bf16 v[20:23], v[162:165], v[196:199], v[20:23]
	v_mfma_f32_16x16x32_bf16 v[16:19], v[172:175], v[196:199], v[16:19]
	v_mfma_f32_16x16x32_bf16 v[4:7], v[162:165], v[214:217], v[4:7]
	v_mfma_f32_16x16x32_bf16 v[0:3], v[172:175], v[214:217], v[0:3]
	v_mfma_f32_16x16x32_bf16 v[56:59], v[176:179], v[184:187], v[48:51]
	v_mfma_f32_16x16x32_bf16 v[36:39], v[168:171], v[192:195], v[36:39]
	v_mfma_f32_16x16x32_bf16 v[32:35], v[176:179], v[192:195], v[32:35]
	v_mfma_f32_16x16x32_bf16 v[20:23], v[168:171], v[210:213], v[20:23]
	v_mfma_f32_16x16x32_bf16 v[16:19], v[176:179], v[210:213], v[16:19]
	v_mfma_f32_16x16x32_bf16 v[4:7], v[168:171], v[218:221], v[4:7]
	v_mfma_f32_16x16x32_bf16 v[0:3], v[176:179], v[218:221], v[0:3]
	s_barrier
	s_add_i32 s39, s39, 2
	s_add_u32 s37, s37, 0x100
	s_addc_u32 s38, s38, 0
	s_add_u32 s12, s12, 0x100
	s_addc_u32 s13, s13, 0
	s_cmpk_gt_u32 s39, 0x55
	s_cbranch_scc0 .LBB0_906
	s_and_b64 vcc, exec, s[6:7]
	s_cbranch_vccz .LBB0_909
	s_barrier
